# GLA units: XOR-swizzled LDS column groups for Vt, KeT (transposed ds_write_b16 stores were 8-way bank-conflicted) and Bc (ds_write_b128 8-way conflicted); writers and readers agree, math unchanged
# speedup vs baseline: 1.0085x; 1.0056x over previous
.LBB0_326:
	s_or_b64 exec, exec, s[0:1]
	v_readlane_b32 s8, v254, 21
	v_readlane_b32 s13, v254, 26
	v_readlane_b32 s15, v254, 28
	v_readlane_b32 s12, v254, 25
	v_readlane_b32 s14, v254, 27
	v_mov_b32_e32 v30, s15
	v_mov_b32_e32 v31, s13
	v_cndmask_b32_e64 v31, v30, v31, s[2:3]
	v_mov_b32_e32 v30, s14
	v_mov_b32_e32 v36, s12
	v_lshlrev_b32_e32 v76, 4, v28
	v_cndmask_b32_e64 v30, v30, v36, s[2:3]
	v_mul_lo_u32 v36, v32, s92
	v_or_b32_e32 v37, v76, v91
	v_add_u32_e32 v36, 0, v36
	s_movk_i32 s0, 0xff72
	v_lshlrev_b32_e32 v73, 3, v25
	v_mad_u64_u32 v[78:79], s[0:1], v32, s0, v[36:37]
	v_lshlrev_b32_e32 v28, 1, v28
	v_lshl_add_u32 v92, v73, 1, v36
	v_mul_lo_u32 v36, v37, s92
	v_and_b32_e32 v37, 2, v28
	v_lshlrev_b32_e32 v28, 1, v29
	v_lshlrev_b32_e32 v29, 1, v91
	v_readlane_b32 s1, v255, 34
	v_ashrrev_i32_e32 v41, 7, v24
	v_readlane_b32 s6, v255, 35
	v_lshlrev_b32_e32 v27, 7, v86
	v_add3_u32 v39, s1, v28, v29
	v_lshl_add_u32 v28, v41, 12, s6
	v_lshlrev_b32_e32 v29, 8, v91
	v_readlane_b32 s0, v255, 33
	v_add3_u32 v42, v28, v29, v34
	v_lshlrev_b32_e32 v28, 8, v32
	v_lshlrev_b32_e32 v44, 2, v73
	v_lshlrev_b32_e32 v80, 1, v27
	v_mov_b32_e32 v81, v3
	v_add3_u32 v79, s0, v36, v72
	s_add_i32 s0, 0, 0x1e400
	v_add3_u32 v94, s6, v28, v44
	v_lshl_add_u64 v[28:29], v[30:31], 0, v[80:81]
	v_ashrrev_i32_e32 v77, 31, v76
	v_add_u32_e32 v38, s0, v34
	v_readlane_b32 s0, v255, 31
	v_lshlrev_b32_e32 v24, 4, v41
	v_lshl_add_u64 v[28:29], v[76:77], 1, v[28:29]
	v_mov_b32_e32 v27, v3
	v_mul_u32_u24_e32 v97, 0x480, v25
	v_add_u32_e32 v40, s0, v34
	v_add_u32_e32 v93, s1, v34
	v_cmp_eq_u32_e32 vcc, 3, v41
	v_cmp_eq_u32_e64 s[0:1], 15, v91
	v_lshl_add_u64 v[82:83], v[28:29], 0, v[26:27]
	v_lshlrev_b32_e32 v25, 1, v97
	v_lshlrev_b32_e32 v26, 1, v32
	v_or_b32_e32 v52, v24, v91
	s_and_b64 s[76:77], vcc, s[0:1]
	v_add_u32_e32 v98, v78, v25
	v_add3_u32 v99, 0, v25, v26
	v_or_b32_e32 v25, 2, v72
	v_mul_lo_u32 v24, v52, s92
	v_cmp_gt_i32_e32 vcc, v72, v52
	v_add3_u32 v100, 0, v24, v72
	v_or_b32_e32 v27, 3, v72
	v_cndmask_b32_e64 v24, v160, 0, vcc
	v_cmp_lt_i32_e32 vcc, v52, v25
	v_or_b32_e32 v26, 4, v72
	v_or_b32_e32 v30, 5, v72
	v_cndmask_b32_e64 v25, v160, 0, vcc
	v_cmp_lt_i32_e32 vcc, v72, v52
	v_or_b32_e32 v31, 7, v72
	v_add_u32_e32 v55, 38, v72
	v_cndmask_b32_e32 v28, 0, v160, vcc
	v_cmp_gt_i32_e32 vcc, v27, v52
	v_or_b32_e32 v27, 6, v72
	v_pack_b32_f16 v24, v24, v28
	v_cndmask_b32_e64 v29, v160, 0, vcc
	v_cmp_gt_i32_e32 vcc, v26, v52
	v_or_b32_e32 v28, 32, v72
	v_pack_b32_f16 v25, v25, v29
	v_cndmask_b32_e64 v26, v160, 0, vcc
	v_cmp_gt_i32_e32 vcc, v30, v52
	v_add_u32_e32 v29, 33, v72
	v_or_b32_e32 v48, 1, v37
	v_cndmask_b32_e64 v30, v160, 0, vcc
	v_cmp_gt_i32_e32 vcc, v27, v52
	v_pack_b32_f16 v26, v26, v30
	v_add_u32_e32 v30, 34, v72
	v_cndmask_b32_e64 v27, v160, 0, vcc
	v_cmp_gt_i32_e32 vcc, v31, v52
	v_lshlrev_b32_e32 v35, 2, v90
	v_readlane_b32 s9, v254, 22
	v_cndmask_b32_e64 v31, v160, 0, vcc
	v_cmp_gt_i32_e32 vcc, v28, v52
	v_pack_b32_f16 v27, v27, v31
	v_add_u32_e32 v31, 36, v72
	v_cndmask_b32_e64 v28, v160, 0, vcc
	v_cmp_gt_i32_e32 vcc, v29, v52
	v_readlane_b32 s0, v255, 37
	v_lshlrev_b32_e32 v45, 4, v37
	v_cndmask_b32_e64 v53, v160, 0, vcc
	v_cmp_gt_i32_e32 vcc, v30, v52
	v_add_u32_e32 v30, 35, v72
	v_lshlrev_b32_e32 v49, 4, v48
	v_cndmask_b32_e64 v29, v160, 0, vcc
	v_cmp_gt_i32_e32 vcc, v30, v52
	v_or_b32_e32 v46, v45, v91
	v_or_b32_e32 v50, v49, v91
	v_cndmask_b32_e64 v54, v160, 0, vcc
	v_cmp_gt_i32_e32 vcc, v31, v52
	v_add_u32_e32 v31, 37, v72
	v_pack_b32_f16 v28, v28, v53
	v_cndmask_b32_e64 v30, v160, 0, vcc
	v_cmp_gt_i32_e32 vcc, v31, v52
	v_add_u32_e32 v101, s0, v44
	v_or_b32_e32 v44, 1, v73
	v_cndmask_b32_e64 v56, v160, 0, vcc
	v_cmp_gt_i32_e32 vcc, v55, v52
	v_add_u32_e32 v55, 39, v72
	v_cmp_le_i32_e64 s[6:7], v37, v41
	v_cndmask_b32_e64 v31, v160, 0, vcc
	v_cmp_gt_i32_e32 vcc, v55, v52
	v_lshlrev_b32_e32 v53, 5, v37
	v_cmp_lt_i32_e64 s[8:9], v37, v41
	v_cndmask_b32_e64 v55, v160, 0, vcc
	v_lshlrev_b32_e32 v41, 5, v48
	v_lshlrev_b32_e32 v37, 6, v37
	v_or_b32_e32 v45, v45, v35
	v_lshlrev_b32_e32 v48, 6, v48
	v_or_b32_e32 v35, v49, v35
	v_readlane_b32 s10, v254, 23
	v_readlane_b32 s11, v254, 24
	v_readlane_b32 s16, v254, 29
	v_readlane_b32 s17, v254, 30
	v_readlane_b32 s18, v254, 31
	v_readlane_b32 s19, v254, 32
	v_readlane_b32 s20, v254, 33
	v_readlane_b32 s21, v254, 34
	v_readlane_b32 s22, v254, 35
	v_readlane_b32 s23, v254, 36
	v_add_u32_e32 v43, s0, v34
	v_add_u32_e32 v36, 0, v36
	v_add_u32_e32 v96, 0, v34
	v_mul_u32_u24_e32 v47, 48, v46
	v_mul_u32_u24_e32 v51, 48, v50
	v_pack_b32_f16 v31, v31, v55
	v_pack_b32_f16 v30, v30, v56
	v_pack_b32_f16 v29, v29, v54
	v_mul_u32_u24_e32 v44, 0x90, v44
	v_mul_u32_u24_e32 v103, 0x90, v91
	v_add_u32_e32 v104, v38, v37
	v_mul_u32_u24_e32 v54, 0x90, v45
	v_or_b32_e32 v55, 2, v45
	v_or_b32_e32 v56, 3, v45
	v_add_u32_e32 v105, v38, v48
	v_mul_u32_u24_e32 v38, 0x90, v35
	v_or_b32_e32 v49, 2, v35
	v_or_b32_e32 v57, 3, v35
	v_sub_u32_e32 v115, 0xbf, v32
	v_add_u32_e32 v116, 64, v32
	v_mov_b32_e32 v32, 0
	v_lshl_add_u32 v95, v72, 1, 0
	v_add_u32_e32 v102, 16, v101
	v_mul_u32_u24_e32 v106, 0x90, v46
	v_add_u32_e32 v107, v42, v37
	v_mul_u32_u24_e32 v108, 0x90, v50
	v_add_u32_e32 v109, v42, v48
	v_cmp_gt_i32_e64 s[10:11], v45, v52
	v_cmp_lt_i32_e64 s[12:13], v45, v52
	v_cmp_gt_i32_e64 s[14:15], v55, v52
	v_cmp_gt_i32_e64 s[16:17], v56, v52
	v_cmp_gt_i32_e64 s[18:19], v35, v52
	v_cmp_lt_i32_e64 s[20:21], v35, v52
	v_cmp_gt_i32_e64 s[22:23], v49, v52
	v_cmp_gt_i32_e64 s[24:25], v57, v52
	v_add_u32_e32 v110, v43, v37
	v_add_u32_e32 v111, v43, v48
	s_mov_b32 s26, 0
	v_sub_u32_e32 v112, 0, v91
	v_add_u32_e32 v113, 64, v33
	v_sub_u32_e32 v114, 0xbf, v33
	v_add_u32_e32 v117, v40, v47
	v_add_u32_e32 v118, v39, v54
	v_add_u32_e32 v119, v40, v51
	v_add_u32_e32 v120, v39, v38
	v_lshlrev_b32_e32 v84, 1, v2
	v_add_u32_e32 v121, v78, v44
	v_add_u32_e32 v122, v100, v53
	v_add_u32_e32 v123, v100, v41
	v_add_u32_e32 v124, v36, v34
	v_add_u32_e32 v125, v96, v103
	s_mov_b32 s27, 0
	s_mov_b32 s28, 0
	v_mov_b32_e32 v33, v32
	v_mov_b32_e32 v34, v32
	v_mov_b32_e32 v35, v32
	v_mov_b32_e32 v44, v32
	v_mov_b32_e32 v45, v32
	v_mov_b32_e32 v46, v32
	v_mov_b32_e32 v47, v32
	v_mov_b32_e32 v40, v32
	v_mov_b32_e32 v41, v32
	v_mov_b32_e32 v42, v32
	v_mov_b32_e32 v43, v32
	v_mov_b32_e32 v36, v32
	v_mov_b32_e32 v37, v32
	v_mov_b32_e32 v38, v32
	v_mov_b32_e32 v39, v32
	v_bfe_u32 v244, v238, 6, 2
	v_and_b32_e32 v245, 3, v238
	v_xor_b32_e32 v245, v244, v245
	v_sub_u32_e32 v245, v245, v244
	v_lshlrev_b32_e32 v247, 4, v245
	v_add_u32_e32 v98, v98, v247
	v_add_u32_e32 v99, v99, v247
	v_add_u32_e32 v121, v121, v247
	v_bfe_u32 v245, v238, 4, 2
	v_xor_b32_e32 v246, v245, v244
	v_sub_u32_e32 v246, v246, v245
	v_lshl_add_u32 v124, v246, 4, v124
	v_bfe_u32 v246, v238, 3, 1
	v_xor_b32_e32 v248, v245, v246
	v_xor_b32_e32 v249, 2, v248
	v_sub_u32_e32 v248, v248, v245
	v_sub_u32_e32 v249, v249, v245
	v_lshl_add_u32 v248, v248, 4, v125
	v_lshl_add_u32 v249, v249, 4, v125
	v_and_b32_e32 v246, 7, v238
	v_xor_b32_e32 v244, v245, v246
	v_sub_u32_e32 v244, v244, v245
	v_lshl_add_u32 v107, v244, 4, v107
	v_or_b32_e32 v245, 4, v245
	v_xor_b32_e32 v244, v245, v246
	v_sub_u32_e32 v244, v244, v245
	v_lshl_add_u32 v109, v244, 4, v109
	v_lshlrev_b32_e32 v245, 1, v246
	v_bfe_u32 v246, v238, 3, 3
	v_xor_b32_e32 v244, v245, v246
	v_sub_u32_e32 v244, v244, v245
	v_or_b32_e32 v245, 1, v245
	v_xor_b32_e32 v246, v245, v246
	v_sub_u32_e32 v246, v246, v245
	v_lshl_add_u32 v250, v246, 4, v94
	v_lshl_add_u32 v94, v244, 4, v94
	s_branch .LBB0_328
.LBB0_327:
	s_or_b64 exec, exec, s[0:1]
	s_nop 5
	v_cvt_f16_f32_e32 v2, v52
	v_cvt_f16_f32_e32 v52, v53
	v_cvt_f16_f32_e32 v53, v54
	v_cvt_f16_f32_e32 v54, v55
	v_cndmask_b32_e64 v2, v2, 0, s[18:19]
	v_cndmask_b32_e64 v52, 0, v52, s[20:21]
	v_cndmask_b32_e64 v53, v53, 0, s[22:23]
	v_cndmask_b32_e64 v54, v54, 0, s[24:25]
	v_pack_b32_f16 v53, v53, v54
	v_pack_b32_f16 v52, v2, v52
	ds_write_b64 v123, v[52:53]
	s_waitcnt lgkmcnt(0)
	s_barrier
	ds_read_b128 v[68:71], v124 offset:55296
	ds_read_b128 v[126:129], v124 offset:55360
	ds_read_b128 v[52:55], v125
	s_waitcnt lgkmcnt(0)
	v_mfma_f32_16x16x32_f16 v[48:51], v[68:71], v[52:55], v[48:51]
	ds_read_b128 v[52:55], v125 offset:64
	v_add_u32_e32 v2, 0x1e500, v96
	s_add_i32 s28, s28, 1
	s_waitcnt lgkmcnt(0)
	v_mfma_f32_16x16x32_f16 v[52:55], v[126:129], v[52:55], v[48:51]
	s_nop 2
	ds_read_b128 v[48:51], v125 offset:2304
	s_waitcnt lgkmcnt(0)
	v_mfma_f32_16x16x32_f16 v[48:51], v[68:71], v[48:51], v[56:59]
	s_nop 2
	ds_read_b128 v[56:59], v125 offset:2368
	v_cvt_pk_f16_f32 v55, v54, v55
	v_cvt_pk_f16_f32 v54, v52, v53
	s_waitcnt lgkmcnt(0)
	v_mfma_f32_16x16x32_f16 v[56:59], v[126:129], v[56:59], v[48:51]
	s_nop 2
	ds_read_b128 v[48:51], v125 offset:4608
	s_waitcnt lgkmcnt(0)
	v_mfma_f32_16x16x32_f16 v[48:51], v[68:71], v[48:51], v[60:63]
	s_nop 2
	ds_read_b128 v[60:63], v125 offset:4672
	s_waitcnt lgkmcnt(0)
	v_mfma_f32_16x16x32_f16 v[60:63], v[126:129], v[60:63], v[48:51]
	s_nop 2
	ds_read_b128 v[48:51], v125 offset:6912
	s_waitcnt lgkmcnt(0)
	v_mfma_f32_16x16x32_f16 v[48:51], v[68:71], v[48:51], v[64:67]
	s_nop 2
	ds_read_b128 v[64:67], v125 offset:6976
	s_waitcnt lgkmcnt(0)
	v_mfma_f32_16x16x32_f16 v[48:51], v[126:129], v[64:67], v[48:51]
	ds_read_b128 v[64:67], v2
	s_waitcnt lgkmcnt(0)
	v_pk_mul_f32 v[44:45], v[44:45], v[64:65]
	v_pk_mul_f32 v[46:47], v[46:47], v[66:67]
	ds_read_b128 v[64:67], v248 offset:46080
	s_nop 2
	v_cvt_pk_f16_f32 v51, v50, v51
	s_waitcnt lgkmcnt(0)
	v_mfma_f32_16x16x32_f16 v[44:47], v[64:67], v[68:71], v[44:47]
	ds_read_b128 v[64:67], v248 offset:46144
	v_cvt_pk_f16_f32 v50, v48, v49
	s_waitcnt lgkmcnt(0)
	v_mfma_f32_16x16x32_f16 v[44:47], v[64:67], v[126:129], v[44:47]
	ds_read_b128 v[64:67], v2 offset:64
	s_waitcnt lgkmcnt(0)
	v_pk_mul_f32 v[32:33], v[32:33], v[64:65]
	v_pk_mul_f32 v[34:35], v[34:35], v[66:67]
	ds_read_b128 v[64:67], v249 offset:48384
	s_waitcnt lgkmcnt(0)
	v_mfma_f32_16x16x32_f16 v[32:35], v[64:67], v[68:71], v[32:35]
	ds_read_b128 v[64:67], v249 offset:48448
	s_waitcnt lgkmcnt(0)
	v_mfma_f32_16x16x32_f16 v[32:35], v[64:67], v[126:129], v[32:35]
	ds_read_b128 v[64:67], v2 offset:128
	s_waitcnt lgkmcnt(0)
	v_pk_mul_f32 v[40:41], v[40:41], v[64:65]
	v_pk_mul_f32 v[42:43], v[42:43], v[66:67]
	ds_read_b128 v[64:67], v248 offset:50688
	s_waitcnt lgkmcnt(0)
	v_mfma_f32_16x16x32_f16 v[40:43], v[64:67], v[68:71], v[40:43]
	ds_read_b128 v[64:67], v248 offset:50752
	s_waitcnt lgkmcnt(0)
	v_mfma_f32_16x16x32_f16 v[40:43], v[64:67], v[126:129], v[40:43]
	ds_read_b128 v[64:67], v2 offset:192
	v_add_u32_e32 v2, s26, v91
	s_add_i32 s26, s26, 64
	s_waitcnt lgkmcnt(0)
	v_pk_mul_f32 v[36:37], v[36:37], v[64:65]
	v_pk_mul_f32 v[38:39], v[38:39], v[66:67]
	ds_read_b128 v[64:67], v249 offset:52992
	s_waitcnt lgkmcnt(0)
	v_mfma_f32_16x16x32_f16 v[36:39], v[64:67], v[68:71], v[36:39]
	ds_read_b128 v[64:67], v249 offset:53056
	s_waitcnt lgkmcnt(0)
	v_mfma_f32_16x16x32_f16 v[36:39], v[64:67], v[126:129], v[36:39]
	v_add_u32_e32 v64, s27, v112
	v_add_u32_e32 v65, 0xff, v64
	v_cndmask_b32_e64 v65, v65, v2, s[2:3]
	v_add_u32_e32 v52, v65, v89
	v_mad_i64_i32 v[52:53], s[0:1], v52, s91, v[82:83]
	global_store_dwordx2 v[52:53], v[54:55], off
	v_add_u32_e32 v52, 16, v2
	v_add_u32_e32 v53, 0xef, v64
	v_cndmask_b32_e64 v54, v53, v52, s[2:3]
	v_add_u32_e32 v54, v54, v89
	v_cvt_pk_f16_f32 v53, v58, v59
	v_cvt_pk_f16_f32 v52, v56, v57
	v_mad_i64_i32 v[54:55], s[0:1], v54, s91, v[82:83]
	global_store_dwordx2 v[54:55], v[52:53], off
	v_add_u32_e32 v52, 32, v2
	v_add_u32_e32 v53, 0xdf, v64
	v_cndmask_b32_e64 v54, v53, v52, s[2:3]
	v_add_u32_e32 v54, v54, v89
	v_cvt_pk_f16_f32 v53, v62, v63
	v_cvt_pk_f16_f32 v52, v60, v61
	v_mad_i64_i32 v[54:55], s[0:1], v54, s91, v[82:83]
	global_store_dwordx2 v[54:55], v[52:53], off
	v_add_u32_e32 v2, 48, v2
	v_add_u32_e32 v52, 0xcf, v64
	v_cndmask_b32_e64 v2, v52, v2, s[2:3]
	v_add_u32_e32 v2, v2, v89
	s_sub_i32 s27, s27, 64
	v_mad_i64_i32 v[48:49], s[0:1], v2, s91, v[82:83]
	s_cmpk_lg_i32 s27, 0xff00
	global_store_dwordx2 v[48:49], v[50:51], off
	s_cbranch_scc0 .LBB0_485

.LBB0_340:
	s_or_b64 exec, exec, s[0:1]
	s_waitcnt lgkmcnt(0)
	s_barrier
	ds_read_b128 v[48:51], v92
	ds_read_b128 v[52:55], v92 offset:9216
	ds_read_b128 v[60:63], v94
	ds_read_b128 v[56:59], v250 offset:16
	ds_read_b128 v[68:71], v101
	v_add_u32_e32 v81, v95, v103
	s_waitcnt lgkmcnt(3)
	v_cvt_f32_f16_sdwa v67, v52 dst_sel:DWORD dst_unused:UNUSED_PAD src0_sel:WORD_1
	s_waitcnt lgkmcnt(2)
	v_mul_f32_e32 v2, 0x3fb8aa3b, v60
	v_exp_f32_e32 v60, v2
	v_mul_f32_e32 v2, 0x3fb8aa3b, v61
	v_exp_f32_e32 v61, v2
	v_cvt_f32_f16_e32 v66, v52
	v_rcp_f32_e32 v64, v60
	v_add3_u32 v52, v78, v97, v247
	v_rcp_f32_e32 v65, v61
	v_cvt_f32_f16_sdwa v127, v54 dst_sel:DWORD dst_unused:UNUSED_PAD src0_sel:WORD_1
	v_cvt_f32_f16_e32 v126, v54
	v_pk_mul_f32 v[66:67], v[64:65], v[66:67]
	v_cvt_f32_f16_sdwa v65, v48 dst_sel:DWORD dst_unused:UNUSED_PAD src0_sel:WORD_1
	v_cvt_f32_f16_e32 v64, v48
	s_waitcnt lgkmcnt(0)
	v_fma_mixlo_f16 v2, v68, v66, 0
	ds_write_b16 v52, v2 offset:46080
	v_fma_mixlo_f16 v2, v69, v67, 0
	v_pk_mul_f32 v[64:65], v[64:65], s[68:69] op_sel_hi:[1,0]
	ds_write_b16 v121, v2 offset:46080
	v_mul_f32_e32 v2, 0x3fb8aa3b, v62
	v_pk_mul_f32 v[64:65], v[64:65], v[60:61]
	v_exp_f32_e32 v60, v2
	v_mul_f32_e32 v2, 0x3fb8aa3b, v63
	v_exp_f32_e32 v61, v2
	v_cvt_f32_f16_sdwa v69, v53 dst_sel:DWORD dst_unused:UNUSED_PAD src0_sel:WORD_1
	v_rcp_f32_e32 v62, v60
	v_cvt_f32_f16_e32 v68, v53
	v_rcp_f32_e32 v63, v61
	v_cvt_f32_f16_sdwa v53, v49 dst_sel:DWORD dst_unused:UNUSED_PAD src0_sel:WORD_1
	v_cvt_f32_f16_e32 v52, v49
	v_cvt_pk_f16_f32 v48, v64, v65
	v_pk_mul_f32 v[68:69], v[62:63], v[68:69]
	v_pk_mul_f32 v[52:53], v[52:53], s[68:69] op_sel_hi:[1,0]
	v_fma_mixlo_f16 v2, v70, v68, 0
	ds_write_b16 v121, v2 offset:46224
	v_fma_mixlo_f16 v2, v71, v69, 0
	ds_write_b16 v121, v2 offset:46368
	v_mul_f32_e32 v2, 0x3fb8aa3b, v56
	v_exp_f32_e32 v56, v2
	v_mul_f32_e32 v2, 0x3fb8aa3b, v57
	v_exp_f32_e32 v57, v2
	v_pk_mul_f32 v[52:53], v[52:53], v[60:61]
	v_rcp_f32_e32 v70, v56
	ds_read_b128 v[60:63], v102
	v_rcp_f32_e32 v71, v57
	v_cvt_pk_f16_f32 v49, v52, v53
	v_pk_mul_f32 v[70:71], v[70:71], v[126:127]
	s_waitcnt lgkmcnt(0)
	v_fma_mixlo_f16 v2, v60, v70, 0
	ds_write_b16 v121, v2 offset:46512
	v_fma_mixlo_f16 v2, v61, v71, 0
	ds_write_b16 v121, v2 offset:46656
	v_mul_f32_e32 v2, 0x3fb8aa3b, v58
	v_cvt_f32_f16_sdwa v127, v50 dst_sel:DWORD dst_unused:UNUSED_PAD src0_sel:WORD_1
	v_cvt_f32_f16_e32 v126, v50
	v_exp_f32_e32 v58, v2
	v_mul_f32_e32 v2, 0x3fb8aa3b, v59
	v_exp_f32_e32 v59, v2
	v_pk_mul_f32 v[126:127], v[126:127], s[68:69] op_sel_hi:[1,0]
	v_cvt_f32_f16_sdwa v61, v55 dst_sel:DWORD dst_unused:UNUSED_PAD src0_sel:WORD_1
	v_pk_mul_f32 v[126:127], v[126:127], v[56:57]
	v_rcp_f32_e32 v56, v58
	v_rcp_f32_e32 v57, v59
	v_cvt_f32_f16_e32 v60, v55
	v_bfe_u32 v55, v71, 16, 1
	v_add3_u32 v55, v71, v55, s34
	v_cvt_pk_f16_f32 v50, v126, v127
	v_pk_mul_f32 v[128:129], v[56:57], v[60:61]
	v_bfe_u32 v56, v70, 16, 1
	v_fma_mixlo_f16 v2, v62, v128, 0
	ds_write_b16 v121, v2 offset:46800
	v_bfe_u32 v2, v129, 16, 1
	v_bfe_u32 v54, v128, 16, 1
	v_bfe_u32 v57, v69, 16, 1
	v_bfe_u32 v60, v68, 16, 1
	v_bfe_u32 v61, v67, 16, 1
	v_bfe_u32 v62, v66, 16, 1
	v_add3_u32 v62, v66, v62, s34
	v_add3_u32 v61, v67, v61, s34
	v_add3_u32 v60, v68, v60, s34
	v_add3_u32 v66, v69, v57, s34
	v_add3_u32 v56, v70, v56, s34
	v_add3_u32 v54, v128, v54, s34
	v_add3_u32 v2, v129, v2, s34
	v_perm_b32 v57, v2, v54, s82
	v_perm_b32 v56, v55, v56, s82
	v_perm_b32 v55, v66, v60, s82
	v_perm_b32 v54, v61, v62, s82
	v_cvt_f32_f16_sdwa v61, v51 dst_sel:DWORD dst_unused:UNUSED_PAD src0_sel:WORD_1
	v_cvt_f32_f16_e32 v60, v51
	v_bfe_u32 v62, v126, 16, 1
	v_bfe_u32 v66, v53, 16, 1
	v_bfe_u32 v67, v52, 16, 1
	v_pk_mul_f32 v[60:61], v[60:61], s[68:69] op_sel_hi:[1,0]
	v_bfe_u32 v68, v65, 16, 1
	v_pk_mul_f32 v[58:59], v[60:61], v[58:59]
	v_bfe_u32 v61, v127, 16, 1
	v_bfe_u32 v2, v59, 16, 1
	v_bfe_u32 v60, v58, 16, 1
	v_cvt_pk_f16_f32 v51, v58, v59
	v_bfe_u32 v69, v64, 16, 1
	v_add3_u32 v58, v58, v60, s34
	v_add3_u32 v2, v59, v2, s34
	v_add3_u32 v64, v64, v69, s34
	v_add3_u32 v65, v65, v68, s34
	v_add3_u32 v52, v52, v67, s34
	v_add3_u32 v53, v53, v66, s34
	v_add3_u32 v62, v126, v62, s34
	v_add3_u32 v66, v127, v61, s34
	v_perm_b32 v61, v2, v58, s82
	v_fma_mixlo_f16 v2, v63, v129, 0
	v_perm_b32 v60, v66, v62, s82
	v_perm_b32 v59, v53, v52, s82
	v_perm_b32 v58, v65, v64, s82
	ds_write_b16 v121, v2 offset:46944
	ds_write_b128 v92, v[58:61] offset:18432
	ds_write_b128 v92, v[54:57] offset:27648
	ds_write_b128 v92, v[48:51] offset:36864
	v_add_u32_e32 v2, v79, v72
	s_waitcnt lgkmcnt(0)
	s_barrier
	ds_read_b128 v[48:51], v2
	ds_read_b128 v[52:55], v81 offset:36864
	ds_read_b128 v[56:59], v81 offset:39168
	ds_read_b128 v[60:63], v81 offset:41472
	ds_read_b128 v[64:67], v81 offset:43776
	s_waitcnt lgkmcnt(3)
	v_mfma_f32_16x16x32_f16 v[52:55], v[48:51], v[52:55], 0
	s_waitcnt lgkmcnt(2)
	v_mfma_f32_16x16x32_f16 v[56:59], v[48:51], v[56:59], 0
	s_waitcnt lgkmcnt(1)
	v_mfma_f32_16x16x32_f16 v[60:63], v[48:51], v[60:63], 0
	s_waitcnt lgkmcnt(0)
	v_mfma_f32_16x16x32_f16 v[64:67], v[48:51], v[64:67], 0
	ds_read_b128 v[68:71], v2 offset:64
	ds_read_b128 v[48:51], v81 offset:36928
	v_add_u32_e32 v2, v100, v72
	s_waitcnt lgkmcnt(0)
	v_mfma_f32_16x16x32_f16 v[48:51], v[68:71], v[48:51], v[52:55]
	s_nop 2
	ds_read_b128 v[52:55], v81 offset:39232
	s_waitcnt lgkmcnt(0)
	v_mfma_f32_16x16x32_f16 v[56:59], v[68:71], v[52:55], v[56:59]
	ds_read_b128 v[52:55], v81 offset:41536
	s_waitcnt lgkmcnt(0)
	v_mfma_f32_16x16x32_f16 v[60:63], v[68:71], v[52:55], v[60:63]
	ds_read_b128 v[52:55], v81 offset:43840
	s_waitcnt lgkmcnt(0)
	v_mfma_f32_16x16x32_f16 v[64:67], v[68:71], v[52:55], v[64:67]
	v_mov_b32_e32 v52, 0
	v_mov_b32_e32 v68, 0
	v_mov_b32_e32 v69, 0
	v_mov_b32_e32 v70, 0
	v_mov_b32_e32 v71, 0
	s_and_saveexec_b64 s[0:1], s[6:7]
	s_cbranch_execz .LBB0_342
	v_add_u32_e32 v53, v95, v106
	ds_read_b128 v[68:71], v2 offset:18432
	ds_read_b128 v[126:129], v53 offset:27648
	s_waitcnt lgkmcnt(0)
	v_mfma_f32_16x16x32_bf16 v[68:71], v[126:129], v[68:71], 0
	ds_read_b128 v[126:129], v2 offset:18496
	ds_read_b128 v[130:133], v53 offset:27712
	s_waitcnt lgkmcnt(0)
	v_mfma_f32_16x16x32_bf16 v[68:71], v[130:133], v[126:129], v[68:71]

.LBB0_420:
	s_or_b64 exec, exec, s[0:1]
	v_readlane_b32 s8, v254, 21
	v_readlane_b32 s13, v254, 26
	v_readlane_b32 s15, v254, 28
	v_lshlrev_b32_e32 v51, 2, v46
	v_readlane_b32 s12, v254, 25
	v_readlane_b32 s14, v254, 27
	v_mov_b32_e32 v45, s15
	v_mov_b32_e32 v46, s13
	v_cndmask_b32_e64 v55, v45, v46, s[2:3]
	v_mov_b32_e32 v45, s14
	v_mov_b32_e32 v46, s12
	v_cndmask_b32_e64 v54, v45, v46, s[2:3]
	v_mul_lo_u32 v45, v82, s92
	v_add_u32_e32 v46, 0, v45
	s_movk_i32 s0, 0xff72
	v_mad_u64_u32 v[72:73], s[0:1], v82, s0, v[46:47]
	v_lshlrev_b32_e32 v1, 3, v47
	v_mul_lo_u32 v43, v43, s92
	v_readlane_b32 s0, v255, 33
	v_lshlrev_b32_e32 v41, 1, v41
	v_and_b32_e32 v56, 2, v41
	v_add3_u32 v73, s0, v43, v0
	s_add_i32 s0, 0, 0x1e400
	v_lshlrev_b32_e32 v41, 1, v53
	v_lshlrev_b32_e32 v45, 1, v80
	v_readlane_b32 s1, v255, 34
	v_ashrrev_i32_e32 v59, 7, v40
	v_readlane_b32 s6, v255, 35
	v_lshlrev_b32_e32 v74, 1, v2
	v_xor_b32_e32 v2, 16, v1
	v_readlane_b32 s9, v254, 22
	v_add_u32_e32 v57, s0, v50
	v_add3_u32 v53, s1, v41, v45
	v_readlane_b32 s0, v255, 31
	v_lshlrev_b32_e32 v41, 4, v59
	v_lshl_add_u32 v45, v59, 12, s6
	v_lshlrev_b32_e32 v60, 8, v80
	v_mov_b32_e32 v75, v3
	v_lshl_add_u32 v88, v2, 1, v46
	v_and_b32_e32 v2, 2, v40
	v_mul_u32_u24_e32 v89, 0x480, v47
	v_add_u32_e32 v58, s0, v50
	v_add_u32_e32 v84, s1, v50
	v_add3_u32 v60, v45, v60, v50
	v_cmp_eq_u32_e32 vcc, 3, v59
	v_cmp_eq_u32_e64 s[0:1], 15, v80
	v_lshlrev_b32_e32 v45, 8, v82
	v_lshlrev_b32_e32 v62, 2, v1
	v_add_u32_e32 v63, 0, v43
	v_lshl_add_u64 v[54:55], v[54:55], 0, v[74:75]
	v_ashrrev_i32_e32 v43, 31, v42
	v_cmp_eq_u32_e64 s[8:9], 0, v2
	v_lshlrev_b32_e32 v2, 1, v89
	v_lshlrev_b32_e32 v40, 1, v82
	v_or_b32_e32 v69, v41, v80
	s_and_b64 s[76:77], vcc, s[0:1]
	v_add3_u32 v85, s6, v45, v62
	v_lshl_add_u64 v[42:43], v[42:43], 1, v[54:55]
	v_mov_b32_e32 v45, v3
	v_add3_u32 v91, 0, v2, v40
	v_or_b32_e32 v40, 2, v0
	v_cmp_gt_i32_e32 vcc, v0, v69
	v_lshl_add_u64 v[76:77], v[42:43], 0, v[44:45]
	v_mul_lo_u32 v41, v69, s92
	v_cndmask_b32_e64 v44, v160, 0, vcc
	v_cmp_lt_i32_e32 vcc, v69, v40
	v_or_b32_e32 v42, 3, v0
	v_add3_u32 v92, 0, v41, v0
	v_cndmask_b32_e64 v40, v160, 0, vcc
	v_cmp_lt_i32_e32 vcc, v0, v69
	v_or_b32_e32 v41, 4, v0
	v_lshl_add_u32 v83, v1, 1, v46
	v_cndmask_b32_e32 v45, 0, v160, vcc
	v_cmp_gt_i32_e32 vcc, v42, v69
	v_or_b32_e32 v43, 5, v0
	v_or_b32_e32 v42, 6, v0
	v_cndmask_b32_e64 v46, v160, 0, vcc
	v_cmp_gt_i32_e32 vcc, v41, v69
	v_cmp_gt_u32_e64 s[6:7], 4, v47
	v_add_u32_e32 v79, 38, v0
	v_cndmask_b32_e64 v41, v160, 0, vcc
	v_cmp_gt_i32_e32 vcc, v43, v69
	v_or_b32_e32 v43, 7, v0
	v_or_b32_e32 v65, 1, v56
	v_cndmask_b32_e64 v47, v160, 0, vcc
	v_cmp_gt_i32_e32 vcc, v42, v69
	v_readlane_b32 s10, v254, 23
	v_readlane_b32 s11, v254, 24
	v_cndmask_b32_e64 v42, v160, 0, vcc
	v_cmp_gt_i32_e32 vcc, v43, v69
	v_readlane_b32 s0, v255, 37
	v_add_u32_e32 v90, v72, v2
	v_cndmask_b32_e64 v43, v160, 0, vcc
	v_pack_b32_f16 v43, v42, v43
	v_pack_b32_f16 v42, v41, v47
	v_pack_b32_f16 v41, v40, v46
	v_pack_b32_f16 v40, v44, v45
	v_or_b32_e32 v44, 32, v0
	v_cmp_gt_i32_e32 vcc, v44, v69
	v_add_u32_e32 v45, 33, v0
	v_add_u32_e32 v46, 34, v0
	v_cndmask_b32_e64 v44, v160, 0, vcc
	v_cmp_gt_i32_e32 vcc, v45, v69
	v_add_u32_e32 v47, 36, v0
	v_lshlrev_b32_e32 v2, 4, v56
	v_cndmask_b32_e64 v75, v160, 0, vcc
	v_cmp_gt_i32_e32 vcc, v46, v69
	v_add_u32_e32 v46, 35, v0
	v_lshlrev_b32_e32 v66, 4, v65
	v_cndmask_b32_e64 v45, v160, 0, vcc
	v_cmp_gt_i32_e32 vcc, v46, v69
	v_or_b32_e32 v55, v2, v80
	v_or_b32_e32 v67, v66, v80
	v_cndmask_b32_e64 v78, v160, 0, vcc
	v_cmp_gt_i32_e32 vcc, v47, v69
	v_add_u32_e32 v47, 37, v0
	v_pack_b32_f16 v44, v44, v75
	v_cndmask_b32_e64 v46, v160, 0, vcc
	v_cmp_gt_i32_e32 vcc, v47, v69
	v_cmp_le_i32_e64 s[10:11], v56, v59
	v_lshlrev_b32_e32 v75, 5, v56
	v_cndmask_b32_e64 v93, v160, 0, vcc
	v_cmp_gt_i32_e32 vcc, v79, v69
	v_add_u32_e32 v79, 39, v0
	v_pack_b32_f16 v46, v46, v93
	v_cndmask_b32_e64 v47, v160, 0, vcc
	v_cmp_gt_i32_e32 vcc, v79, v69
	v_add_u32_e32 v93, s0, v62
	v_or_b32_e32 v62, 1, v1
	v_cndmask_b32_e64 v79, v160, 0, vcc
	v_cmp_lt_i32_e64 s[12:13], v56, v59
	v_lshlrev_b32_e32 v59, 5, v65
	v_lshlrev_b32_e32 v56, 6, v56
	v_or_b32_e32 v2, v2, v51
	v_lshlrev_b32_e32 v65, 6, v65
	v_or_b32_e32 v51, v66, v51
	v_readlane_b32 s16, v254, 29
	v_readlane_b32 s17, v254, 30
	v_readlane_b32 s18, v254, 31
	v_readlane_b32 s19, v254, 32
	v_readlane_b32 s20, v254, 33
	v_readlane_b32 s21, v254, 34
	v_readlane_b32 s22, v254, 35
	v_readlane_b32 s23, v254, 36
	v_add_u32_e32 v61, s0, v50
	v_add_u32_e32 v87, 0, v50
	v_and_b32_e32 v54, 8, v1
	v_mul_u32_u24_e32 v64, 48, v55
	v_mul_u32_u24_e32 v68, 48, v67
	v_pack_b32_f16 v47, v47, v79
	v_pack_b32_f16 v45, v45, v78
	v_mul_u32_u24_e32 v62, 0x90, v62
	v_mul_u32_u24_e32 v95, 0x90, v80
	v_add_u32_e32 v96, v57, v56
	v_mul_u32_u24_e32 v78, 0x90, v2
	v_or_b32_e32 v79, 2, v2
	v_or_b32_e32 v102, 3, v2
	v_add_u32_e32 v97, v57, v65
	v_mul_u32_u24_e32 v57, 0x90, v51
	v_or_b32_e32 v66, 2, v51
	v_or_b32_e32 v103, 3, v51
	v_lshl_add_u32 v86, v0, 1, 0
	s_mov_b32 s78, 0
	v_add_u32_e32 v94, 16, v93
	v_mul_u32_u24_e32 v98, 0x90, v55
	v_add_u32_e32 v99, v60, v56
	v_mul_u32_u24_e32 v100, 0x90, v67
	v_add_u32_e32 v101, v60, v65
	v_cmp_gt_i32_e64 s[14:15], v2, v69
	v_cmp_lt_i32_e64 s[16:17], v2, v69
	v_cmp_gt_i32_e64 s[18:19], v79, v69
	v_cmp_gt_i32_e64 s[20:21], v102, v69
	v_cmp_gt_i32_e64 s[22:23], v51, v69
	v_cmp_lt_i32_e64 s[24:25], v51, v69
	v_cmp_gt_i32_e64 s[26:27], v66, v69
	v_cmp_gt_i32_e64 s[28:29], v103, v69
	v_add_u32_e32 v102, v61, v56
	v_add_u32_e32 v103, v61, v65
	v_sub_u32_e32 v104, 0, v80
	v_sub_u32_e32 v105, 0, v82
	v_add_u32_e32 v106, 64, v49
	v_sub_u32_e32 v107, 0x7bf, v49
	v_add_u32_e32 v108, v58, v64
	v_add_u32_e32 v109, v53, v78
	v_add_u32_e32 v110, v58, v68
	v_add_u32_e32 v111, v53, v57
	v_lshlrev_b32_e32 v2, 1, v52
	v_lshlrev_b32_e32 v78, 1, v48
	v_lshlrev_b32_e32 v112, 2, v54
	v_add_u32_e32 v113, v72, v62
	v_add_u32_e32 v114, v92, v75
	v_add_u32_e32 v115, v92, v59
	v_add_u32_e32 v116, v63, v50
	v_add_u32_e32 v117, v87, v95
	s_mov_b32 s79, 0
	s_mov_b32 s30, 0
	v_bfe_u32 v244, v238, 6, 2
	v_and_b32_e32 v245, 3, v238
	v_xor_b32_e32 v245, v244, v245
	v_sub_u32_e32 v245, v245, v244
	v_lshlrev_b32_e32 v247, 4, v245
	v_add_u32_e32 v90, v90, v247
	v_add_u32_e32 v91, v91, v247
	v_add_u32_e32 v113, v113, v247
	v_bfe_u32 v245, v238, 4, 2
	v_xor_b32_e32 v246, v245, v244
	v_sub_u32_e32 v246, v246, v245
	v_lshl_add_u32 v116, v246, 4, v116
	v_bfe_u32 v246, v238, 3, 1
	v_xor_b32_e32 v248, v245, v246
	v_xor_b32_e32 v249, 2, v248
	v_sub_u32_e32 v248, v248, v245
	v_sub_u32_e32 v249, v249, v245
	v_lshl_add_u32 v248, v248, 4, v117
	v_lshl_add_u32 v249, v249, 4, v117
	v_and_b32_e32 v246, 7, v238
	v_xor_b32_e32 v244, v245, v246
	v_sub_u32_e32 v244, v244, v245
	v_lshl_add_u32 v99, v244, 4, v99
	v_or_b32_e32 v245, 4, v245
	v_xor_b32_e32 v244, v245, v246
	v_sub_u32_e32 v244, v244, v245
	v_lshl_add_u32 v101, v244, 4, v101
	v_lshlrev_b32_e32 v245, 1, v246
	v_bfe_u32 v246, v238, 3, 3
	v_xor_b32_e32 v244, v245, v246
	v_sub_u32_e32 v244, v244, v245
	v_or_b32_e32 v245, 1, v245
	v_xor_b32_e32 v246, v245, v246
	v_sub_u32_e32 v246, v246, v245
	v_lshl_add_u32 v250, v246, 4, v85
	v_lshl_add_u32 v85, v244, 4, v85
	s_branch .LBB0_422
.LBB0_421:
	s_or_b64 exec, exec, s[0:1]
	s_nop 5
	v_cvt_f16_f32_e32 v65, v65
	v_cvt_f16_f32_e32 v64, v64
	s_add_i32 s30, s30, 1
	v_cndmask_b32_e64 v68, 0, v65, s[24:25]
	v_cvt_f16_f32_e32 v65, v66
	v_cvt_f16_f32_e32 v66, v67
	v_cndmask_b32_e64 v64, v64, 0, s[22:23]
	v_pack_b32_f16 v64, v64, v68
	v_cndmask_b32_e64 v65, v65, 0, s[26:27]
	v_cndmask_b32_e64 v66, v66, 0, s[28:29]
	v_pack_b32_f16 v65, v65, v66
	ds_write_b64 v115, v[64:65]
	s_waitcnt lgkmcnt(0)
	s_barrier
	ds_read_b128 v[64:67], v116 offset:55296
	ds_read_b128 v[118:121], v116 offset:55360
	ds_read_b128 v[122:125], v117
	s_waitcnt lgkmcnt(0)
	v_mfma_f32_16x16x32_f16 v[52:55], v[64:67], v[122:125], v[52:55]
	ds_read_b128 v[122:125], v117 offset:64
	v_add_u32_e32 v68, 0x1e500, v87
	s_waitcnt lgkmcnt(0)
	v_mfma_f32_16x16x32_f16 v[52:55], v[118:121], v[122:125], v[52:55]
	ds_read_b128 v[122:125], v117 offset:2304
	s_waitcnt lgkmcnt(0)
	v_mfma_f32_16x16x32_f16 v[56:59], v[64:67], v[122:125], v[56:59]
	ds_read_b128 v[122:125], v117 offset:2368
	s_nop 3
	v_cvt_pk_f16_f32 v55, v54, v55
	v_cvt_pk_f16_f32 v54, v52, v53
	s_waitcnt lgkmcnt(0)
	v_mfma_f32_16x16x32_f16 v[56:59], v[118:121], v[122:125], v[56:59]
	ds_read_b128 v[122:125], v117 offset:4608
	s_waitcnt lgkmcnt(0)
	v_mfma_f32_16x16x32_f16 v[60:63], v[64:67], v[122:125], v[60:63]
	ds_read_b128 v[122:125], v117 offset:4672
	s_waitcnt lgkmcnt(0)
	v_mfma_f32_16x16x32_f16 v[60:63], v[118:121], v[122:125], v[60:63]
	ds_read_b128 v[122:125], v117 offset:6912
	s_waitcnt lgkmcnt(0)
	v_mfma_f32_16x16x32_f16 v[48:51], v[64:67], v[122:125], v[48:51]
	ds_read_b128 v[122:125], v117 offset:6976
	s_waitcnt lgkmcnt(0)
	v_mfma_f32_16x16x32_f16 v[48:51], v[118:121], v[122:125], v[48:51]
	ds_read_b128 v[122:125], v68
	s_waitcnt lgkmcnt(0)
	v_pk_mul_f32 v[8:9], v[8:9], v[122:123]
	v_pk_mul_f32 v[10:11], v[10:11], v[124:125]
	ds_read_b128 v[122:125], v248 offset:46080
	s_nop 2
	v_cvt_pk_f16_f32 v51, v50, v51
	s_waitcnt lgkmcnt(0)
	v_mfma_f32_16x16x32_f16 v[8:11], v[122:125], v[64:67], v[8:11]
	ds_read_b128 v[122:125], v248 offset:46144
	v_cvt_pk_f16_f32 v50, v48, v49
	s_waitcnt lgkmcnt(0)
	v_mfma_f32_16x16x32_f16 v[8:11], v[122:125], v[118:121], v[8:11]
	ds_read_b128 v[122:125], v68 offset:64
	s_waitcnt lgkmcnt(0)
	v_pk_mul_f32 v[4:5], v[4:5], v[122:123]
	v_pk_mul_f32 v[6:7], v[6:7], v[124:125]
	ds_read_b128 v[122:125], v249 offset:48384
	s_waitcnt lgkmcnt(0)
	v_mfma_f32_16x16x32_f16 v[4:7], v[122:125], v[64:67], v[4:7]
	ds_read_b128 v[122:125], v249 offset:48448
	s_waitcnt lgkmcnt(0)
	v_mfma_f32_16x16x32_f16 v[4:7], v[122:125], v[118:121], v[4:7]
	ds_read_b128 v[122:125], v68 offset:128
	s_waitcnt lgkmcnt(0)
	v_pk_mul_f32 v[16:17], v[16:17], v[122:123]
	v_pk_mul_f32 v[18:19], v[18:19], v[124:125]
	ds_read_b128 v[122:125], v248 offset:50688
	s_waitcnt lgkmcnt(0)
	v_mfma_f32_16x16x32_f16 v[16:19], v[122:125], v[64:67], v[16:19]
	ds_read_b128 v[122:125], v248 offset:50752
	s_waitcnt lgkmcnt(0)
	v_mfma_f32_16x16x32_f16 v[16:19], v[122:125], v[118:121], v[16:19]
	ds_read_b128 v[122:125], v68 offset:192
	s_waitcnt lgkmcnt(0)
	v_pk_mul_f32 v[12:13], v[12:13], v[122:123]
	v_pk_mul_f32 v[14:15], v[14:15], v[124:125]
	ds_read_b128 v[122:125], v249 offset:52992
	s_waitcnt lgkmcnt(0)
	v_mfma_f32_16x16x32_f16 v[12:15], v[122:125], v[64:67], v[12:15]
	ds_read_b128 v[64:67], v249 offset:53056
	s_waitcnt lgkmcnt(0)
	v_mfma_f32_16x16x32_f16 v[12:15], v[64:67], v[118:121], v[12:15]
	v_add_u32_e32 v65, s79, v104
	v_add_u32_e32 v64, s78, v80
	v_add_u32_e32 v66, 0x7ff, v65
	v_cndmask_b32_e64 v66, v66, v64, s[2:3]
	v_add_u32_e32 v52, v66, v81
	v_mad_i64_i32 v[52:53], s[0:1], v52, s91, v[76:77]
	global_store_dwordx2 v[52:53], v[54:55], off
	v_add_u32_e32 v52, 16, v64
	v_add_u32_e32 v53, 0x7ef, v65
	v_cndmask_b32_e64 v54, v53, v52, s[2:3]
	v_add_u32_e32 v54, v54, v81
	v_cvt_pk_f16_f32 v53, v58, v59
	v_cvt_pk_f16_f32 v52, v56, v57
	v_mad_i64_i32 v[54:55], s[0:1], v54, s91, v[76:77]
	global_store_dwordx2 v[54:55], v[52:53], off
	v_add_u32_e32 v52, 32, v64
	v_add_u32_e32 v53, 0x7df, v65
	v_cndmask_b32_e64 v54, v53, v52, s[2:3]
	v_add_u32_e32 v54, v54, v81
	v_cvt_pk_f16_f32 v53, v62, v63
	v_cvt_pk_f16_f32 v52, v60, v61
	v_mad_i64_i32 v[54:55], s[0:1], v54, s91, v[76:77]
	global_store_dwordx2 v[54:55], v[52:53], off
	v_add_u32_e32 v52, 48, v64
	v_add_u32_e32 v53, 0x7cf, v65
	v_cndmask_b32_e64 v52, v53, v52, s[2:3]
	v_add_u32_e32 v48, v52, v81
	s_sub_i32 s79, s79, 64
	s_add_i32 s78, s78, 64
	v_mad_i64_i32 v[48:49], s[0:1], v48, s91, v[76:77]
	s_cmpk_lg_i32 s79, 0xf800
	global_store_dwordx2 v[48:49], v[50:51], off
	s_cbranch_scc0 .LBB0_438

.LBB0_434:
	s_or_b64 exec, exec, s[0:1]
	v_add_u32_e32 v57, s78, v82
	v_add_u32_e32 v56, 0x7ff, v56
	v_cndmask_b32_e64 v56, v56, v57, s[2:3]
	s_waitcnt lgkmcnt(0)
	s_barrier
	ds_read_b128 v[58:61], v83
	ds_read_b128 v[48:51], v83 offset:9216
	ds_read_b128 v[62:65], v88
	ds_read_b128 v[52:55], v88 offset:9216
	v_lshrrev_b32_e32 v57, 6, v56
	v_and_b32_e32 v56, 63, v56
	v_cndmask_b32_e64 v56, v56, v57, s[6:7]
	v_lshl_or_b32 v57, v56, 6, v112
	ds_read_b128 v[66:69], v85
	ds_read_b128 v[118:121], v250 offset:16
	v_add_u32_e32 v75, s83, v57
	s_add_i32 s0, 0, 0x1f600
	v_add_u32_e32 v79, s0, v57
	ds_read_b128 v[122:125], v75
	ds_read_b128 v[126:129], v79
	s_waitcnt lgkmcnt(5)
	v_cvt_f32_f16_sdwa v137, v62 dst_sel:DWORD dst_unused:UNUSED_PAD src0_sel:WORD_1
	v_cvt_f32_f16_e32 v136, v62
	v_or_b32_e32 v57, 16, v57
	v_cvt_f32_f16_sdwa v135, v58 dst_sel:DWORD dst_unused:UNUSED_PAD src0_sel:WORD_1
	v_cvt_f32_f16_e32 v134, v58
	s_waitcnt lgkmcnt(3)
	v_mul_f32_e32 v56, 0x3fb8aa3b, v66
	v_add_u32_e32 v140, s83, v57
	v_add_u32_e32 v141, s0, v57
	v_mul_f32_e32 v57, 0x3fb8aa3b, v67
	v_exp_f32_e32 v56, v56
	v_exp_f32_e32 v57, v57
	v_pk_mul_f32 v[136:137], v[136:137], s[68:69] op_sel_hi:[1,0]
	v_pk_mul_f32 v[134:135], v[134:135], s[68:69] op_sel_hi:[1,0]
	s_waitcnt lgkmcnt(0)
	v_pk_mul_f32 v[136:137], v[136:137], v[126:127]
	v_rcp_f32_e32 v66, v56
	v_cndmask_b32_e64 v137, v137, -v137, s[8:9]
	v_cndmask_b32_e64 v136, v136, -v136, s[8:9]
	v_pk_fma_f32 v[134:135], v[134:135], v[122:123], v[136:137]
	v_cvt_f32_f16_sdwa v137, v48 dst_sel:DWORD dst_unused:UNUSED_PAD src0_sel:WORD_1
	v_pk_mul_f32 v[138:139], v[134:135], v[56:57]
	v_cvt_f32_f16_sdwa v135, v52 dst_sel:DWORD dst_unused:UNUSED_PAD src0_sel:WORD_1
	v_cvt_f32_f16_e32 v134, v52
	v_cvt_f32_f16_e32 v136, v48
	ds_read_b128 v[130:133], v93
	v_rcp_f32_e32 v67, v57
	v_pk_mul_f32 v[126:127], v[126:127], v[134:135]
	v_add3_u32 v52, v72, v89, v247
	v_cndmask_b32_e64 v127, v127, -v127, s[8:9]
	v_cndmask_b32_e64 v126, v126, -v126, s[8:9]
	v_pk_fma_f32 v[122:123], v[122:123], v[136:137], v[126:127]
	ds_read_b128 v[134:137], v94
	v_pk_mul_f32 v[126:127], v[122:123], v[66:67]
	v_cvt_f32_f16_e32 v58, v63
	s_waitcnt lgkmcnt(1)
	v_fma_mixlo_f16 v48, v130, v126, 0
	ds_write_b16 v52, v48 offset:46080
	v_fma_mixlo_f16 v48, v131, v127, 0
	ds_write_b16 v113, v48 offset:46080
	v_mul_f32_e32 v48, 0x3fb8aa3b, v68
	v_exp_f32_e32 v66, v48
	v_mul_f32_e32 v48, 0x3fb8aa3b, v69
	v_cvt_f32_f16_sdwa v69, v59 dst_sel:DWORD dst_unused:UNUSED_PAD src0_sel:WORD_1
	v_cvt_f32_f16_e32 v68, v59
	v_cvt_f32_f16_sdwa v59, v63 dst_sel:DWORD dst_unused:UNUSED_PAD src0_sel:WORD_1
	v_exp_f32_e32 v67, v48
	v_cvt_f32_f16_e32 v52, v49
	v_pk_mul_f32 v[68:69], v[68:69], s[68:69] op_sel_hi:[1,0]
	v_pk_mul_f32 v[58:59], v[58:59], s[68:69] op_sel_hi:[1,0]
	v_rcp_f32_e32 v62, v66
	v_pk_mul_f32 v[58:59], v[58:59], v[128:129]
	v_rcp_f32_e32 v63, v67
	v_cndmask_b32_e64 v59, v59, -v59, s[8:9]
	v_cndmask_b32_e64 v58, v58, -v58, s[8:9]
	v_pk_fma_f32 v[58:59], v[68:69], v[124:125], v[58:59]
	v_cvt_pk_f16_f32 v56, v138, v139
	v_pk_mul_f32 v[130:131], v[58:59], v[66:67]
	v_cvt_f32_f16_sdwa v59, v53 dst_sel:DWORD dst_unused:UNUSED_PAD src0_sel:WORD_1
	v_cvt_f32_f16_e32 v58, v53
	v_cvt_f32_f16_sdwa v53, v49 dst_sel:DWORD dst_unused:UNUSED_PAD src0_sel:WORD_1
	v_cvt_pk_f16_f32 v57, v130, v131
	v_pk_mul_f32 v[48:49], v[128:129], v[58:59]
	s_nop 0
	v_cndmask_b32_e64 v49, v49, -v49, s[8:9]
	v_cndmask_b32_e64 v48, v48, -v48, s[8:9]
	v_pk_fma_f32 v[48:49], v[124:125], v[52:53], v[48:49]
	v_cvt_f32_f16_sdwa v59, v60 dst_sel:DWORD dst_unused:UNUSED_PAD src0_sel:WORD_1
	v_pk_mul_f32 v[48:49], v[48:49], v[62:63]
	v_cvt_f32_f16_sdwa v63, v64 dst_sel:DWORD dst_unused:UNUSED_PAD src0_sel:WORD_1
	v_fma_mixlo_f16 v52, v132, v48, 0
	ds_write_b16 v113, v52 offset:46224
	v_fma_mixlo_f16 v52, v133, v49, 0
	ds_write_b16 v113, v52 offset:46368
	ds_read_b128 v[66:69], v140
	ds_read_b128 v[122:125], v141
	v_cvt_f32_f16_e32 v62, v64
	v_cvt_f32_f16_e32 v58, v60
	v_mul_f32_e32 v52, 0x3fb8aa3b, v118
	v_mul_f32_e32 v53, 0x3fb8aa3b, v119
	v_pk_mul_f32 v[62:63], v[62:63], s[68:69] op_sel_hi:[1,0]
	v_exp_f32_e32 v52, v52
	s_waitcnt lgkmcnt(0)
	v_pk_mul_f32 v[62:63], v[62:63], v[122:123]
	v_exp_f32_e32 v53, v53
	v_pk_mul_f32 v[58:59], v[58:59], s[68:69] op_sel_hi:[1,0]
	v_cndmask_b32_e64 v63, v63, -v63, s[8:9]
	v_cndmask_b32_e64 v62, v62, -v62, s[8:9]
	v_pk_fma_f32 v[58:59], v[58:59], v[66:67], v[62:63]
	v_cvt_f32_f16_sdwa v63, v54 dst_sel:DWORD dst_unused:UNUSED_PAD src0_sel:WORD_1
	v_cvt_f32_f16_e32 v62, v54
	v_cvt_f32_f16_sdwa v129, v50 dst_sel:DWORD dst_unused:UNUSED_PAD src0_sel:WORD_1
	v_cvt_f32_f16_e32 v128, v50
	v_rcp_f32_e32 v118, v52
	v_rcp_f32_e32 v119, v53
	v_pk_mul_f32 v[62:63], v[122:123], v[62:63]
	v_cvt_f32_f16_e32 v60, v65
	v_cndmask_b32_e64 v63, v63, -v63, s[8:9]
	v_cndmask_b32_e64 v62, v62, -v62, s[8:9]
	v_pk_fma_f32 v[62:63], v[66:67], v[128:129], v[62:63]
	v_pk_mul_f32 v[52:53], v[58:59], v[52:53]
	v_pk_mul_f32 v[66:67], v[62:63], v[118:119]
	v_cvt_f32_f16_sdwa v119, v61 dst_sel:DWORD dst_unused:UNUSED_PAD src0_sel:WORD_1
	v_fma_mixlo_f16 v50, v134, v66, 0
	v_cvt_f32_f16_e32 v118, v61
	v_cvt_f32_f16_sdwa v61, v65 dst_sel:DWORD dst_unused:UNUSED_PAD src0_sel:WORD_1
	ds_write_b16 v113, v50 offset:46512
	v_fma_mixlo_f16 v50, v135, v67, 0
	ds_write_b16 v113, v50 offset:46656
	v_mul_f32_e32 v50, 0x3fb8aa3b, v120
	v_exp_f32_e32 v62, v50
	v_mul_f32_e32 v50, 0x3fb8aa3b, v121
	v_exp_f32_e32 v63, v50
	v_pk_mul_f32 v[60:61], v[60:61], s[68:69] op_sel_hi:[1,0]
	v_pk_mul_f32 v[118:119], v[118:119], s[68:69] op_sel_hi:[1,0]
	v_pk_mul_f32 v[60:61], v[60:61], v[124:125]
	v_rcp_f32_e32 v64, v62
	v_cndmask_b32_e64 v61, v61, -v61, s[8:9]
	v_cndmask_b32_e64 v60, v60, -v60, s[8:9]
	v_pk_fma_f32 v[60:61], v[118:119], v[68:69], v[60:61]
	v_rcp_f32_e32 v65, v63
	v_pk_mul_f32 v[60:61], v[60:61], v[62:63]
	v_bfe_u32 v62, v131, 16, 1
	v_bfe_u32 v63, v130, 16, 1
	v_bfe_u32 v75, v53, 16, 1
	v_bfe_u32 v79, v52, 16, 1
	v_cvt_pk_f16_f32 v58, v52, v53
	v_bfe_u32 v50, v61, 16, 1
	v_add3_u32 v120, v130, v63, s34
	v_add3_u32 v62, v131, v62, s34
	v_add3_u32 v52, v52, v79, s34
	v_add3_u32 v53, v53, v75, s34
	v_cvt_pk_f16_f32 v59, v60, v61
	v_bfe_u32 v54, v60, 16, 1
	v_add3_u32 v50, v61, v50, s34
	v_perm_b32 v61, v62, v120, s82
	v_perm_b32 v62, v53, v52, s82
	v_cvt_f32_f16_sdwa v53, v55 dst_sel:DWORD dst_unused:UNUSED_PAD src0_sel:WORD_1
	v_cvt_f32_f16_e32 v52, v55
	v_add3_u32 v54, v60, v54, s34
	v_perm_b32 v63, v50, v54, s82
	v_cvt_f32_f16_sdwa v55, v51 dst_sel:DWORD dst_unused:UNUSED_PAD src0_sel:WORD_1
	v_cvt_f32_f16_e32 v54, v51
	v_pk_mul_f32 v[50:51], v[124:125], v[52:53]
	v_bfe_u32 v118, v139, 16, 1
	v_cndmask_b32_e64 v51, v51, -v51, s[8:9]
	v_cndmask_b32_e64 v50, v50, -v50, s[8:9]
	v_pk_fma_f32 v[50:51], v[68:69], v[54:55], v[50:51]
	v_bfe_u32 v119, v138, 16, 1
	v_pk_mul_f32 v[52:53], v[50:51], v[64:65]
	v_bfe_u32 v51, v48, 16, 1
	v_fma_mixlo_f16 v50, v136, v52, 0
	v_bfe_u32 v54, v53, 16, 1
	v_bfe_u32 v55, v52, 16, 1
	ds_write_b16 v113, v50 offset:46800
	v_bfe_u32 v50, v49, 16, 1
	v_bfe_u32 v64, v67, 16, 1
	v_bfe_u32 v65, v66, 16, 1
	v_bfe_u32 v68, v127, 16, 1
	v_bfe_u32 v69, v126, 16, 1
	v_add3_u32 v52, v52, v55, s34
	v_add3_u32 v54, v53, v54, s34
	v_add3_u32 v60, v138, v119, s34
	v_add3_u32 v118, v139, v118, s34
	v_add3_u32 v48, v48, v51, s34
	v_add3_u32 v49, v49, v50, s34
	v_add3_u32 v55, v126, v69, s34
	v_add3_u32 v68, v127, v68, s34
	v_add3_u32 v50, v66, v65, s34
	v_add3_u32 v64, v67, v64, s34
	v_perm_b32 v51, v54, v52, s82
	v_fma_mixlo_f16 v52, v137, v53, 0
	v_perm_b32 v60, v118, v60, s82
	v_perm_b32 v49, v49, v48, s82
	v_perm_b32 v50, v64, v50, s82
	v_perm_b32 v48, v68, v55, s82
	ds_write_b16 v113, v52 offset:46944
	ds_write_b128 v83, v[60:63] offset:18432
	ds_write_b128 v83, v[48:51] offset:27648
	ds_write_b128 v83, v[56:59] offset:36864
	v_add_u32_e32 v56, v73, v0
	s_waitcnt lgkmcnt(0)
	s_barrier
	ds_read_b128 v[48:51], v56
	v_add_u32_e32 v68, v86, v95
	ds_read_b128 v[52:55], v68 offset:36864
	ds_read_b128 v[64:67], v56 offset:64
	ds_read_b128 v[56:59], v68 offset:36928
	ds_read_b128 v[60:63], v68 offset:39168
	ds_read_b128 v[118:121], v68 offset:39232
	ds_read_b128 v[122:125], v68 offset:41472
	ds_read_b128 v[126:129], v68 offset:41536
	ds_read_b128 v[130:133], v68 offset:43776
	ds_read_b128 v[134:137], v68 offset:43840
	s_waitcnt lgkmcnt(8)
	v_mfma_f32_16x16x32_f16 v[52:55], v[48:51], v[52:55], 0
	v_add_u32_e32 v75, v92, v0
	v_mov_b32_e32 v68, 0
	v_mov_b32_e32 v69, 0
	s_waitcnt lgkmcnt(5)
	v_mfma_f32_16x16x32_f16 v[60:63], v[48:51], v[60:63], 0
	s_waitcnt lgkmcnt(3)
	v_mfma_f32_16x16x32_f16 v[122:125], v[48:51], v[122:125], 0
	s_waitcnt lgkmcnt(1)
	v_mfma_f32_16x16x32_f16 v[48:51], v[48:51], v[130:133], 0
	v_mfma_f32_16x16x32_f16 v[52:55], v[64:67], v[56:59], v[52:55]
	v_mfma_f32_16x16x32_f16 v[56:59], v[64:67], v[118:121], v[60:63]
	v_mfma_f32_16x16x32_f16 v[60:63], v[64:67], v[126:129], v[122:125]
	s_waitcnt lgkmcnt(0)
	v_mfma_f32_16x16x32_f16 v[48:51], v[64:67], v[134:137], v[48:51]
	v_mov_b32_e32 v64, 0
	v_mov_b32_e32 v66, 0
	v_mov_b32_e32 v67, 0
	s_and_saveexec_b64 s[0:1], s[10:11]
	s_cbranch_execz .LBB0_436
	v_add_u32_e32 v65, v86, v98
	ds_read_b128 v[66:69], v75 offset:18432
	ds_read_b128 v[118:121], v65 offset:27648
	s_waitcnt lgkmcnt(0)
	v_mfma_f32_16x16x32_bf16 v[66:69], v[118:121], v[66:69], 0
	ds_read_b128 v[118:121], v75 offset:18496
	ds_read_b128 v[122:125], v65 offset:27712
	s_waitcnt lgkmcnt(0)
	v_mfma_f32_16x16x32_bf16 v[66:69], v[122:125], v[118:121], v[66:69]

.LBB0_899:
	s_or_b64 exec, exec, s[0:1]
	v_readlane_b32 s8, v254, 21
	v_readlane_b32 s13, v254, 26
	v_readlane_b32 s15, v254, 28
	v_readlane_b32 s12, v254, 25
	v_readlane_b32 s14, v254, 27
	v_mov_b32_e32 v30, s15
	v_mov_b32_e32 v31, s13
	v_cndmask_b32_e64 v31, v30, v31, s[2:3]
	v_mov_b32_e32 v30, s14
	v_mov_b32_e32 v36, s12
	v_lshlrev_b32_e32 v76, 4, v28
	v_cndmask_b32_e64 v30, v30, v36, s[2:3]
	v_mul_lo_u32 v36, v32, s89
	v_or_b32_e32 v37, v76, v91
	v_add_u32_e32 v36, 0, v36
	s_movk_i32 s0, 0xff72
	v_lshlrev_b32_e32 v73, 3, v25
	v_mad_u64_u32 v[78:79], s[0:1], v32, s0, v[36:37]
	v_lshl_add_u32 v92, v73, 1, v36
	v_mul_lo_u32 v36, v37, s89
	v_readlane_b32 s0, v255, 43
	v_lshlrev_b32_e32 v28, 1, v28
	v_and_b32_e32 v37, 2, v28
	v_add3_u32 v79, s0, v36, v72
	s_add_i32 s0, 0, 0x1e400
	v_add_u32_e32 v38, s0, v34
	v_lshlrev_b32_e32 v28, 1, v29
	v_lshlrev_b32_e32 v29, 1, v91
	v_readlane_b32 s0, v255, 33
	v_ashrrev_i32_e32 v41, 7, v24
	v_readlane_b32 s6, v255, 34
	v_lshlrev_b32_e32 v27, 7, v86
	v_add3_u32 v39, s0, v28, v29
	v_lshl_add_u32 v28, v41, 12, s6
	v_lshlrev_b32_e32 v29, 8, v91
	v_add3_u32 v42, v28, v29, v34
	v_lshlrev_b32_e32 v28, 8, v32
	v_lshlrev_b32_e32 v44, 2, v73
	v_lshlrev_b32_e32 v80, 1, v27
	v_mov_b32_e32 v81, v3
	v_add3_u32 v94, s6, v28, v44
	v_lshl_add_u64 v[28:29], v[30:31], 0, v[80:81]
	v_ashrrev_i32_e32 v77, 31, v76
	v_lshlrev_b32_e32 v24, 4, v41
	v_lshl_add_u64 v[28:29], v[76:77], 1, v[28:29]
	v_mov_b32_e32 v27, v3
	v_mul_u32_u24_e32 v97, 0x480, v25
	v_add_u32_e32 v93, s0, v34
	v_cmp_eq_u32_e32 vcc, 3, v41
	v_cmp_eq_u32_e64 s[0:1], 15, v91
	v_lshl_add_u64 v[82:83], v[28:29], 0, v[26:27]
	v_lshlrev_b32_e32 v25, 1, v97
	v_lshlrev_b32_e32 v26, 1, v32
	v_or_b32_e32 v52, v24, v91
	s_and_b64 s[68:69], vcc, s[0:1]
	v_add_u32_e32 v98, v78, v25
	v_add3_u32 v99, 0, v25, v26
	v_or_b32_e32 v25, 2, v72
	v_mul_lo_u32 v24, v52, s89
	v_cmp_gt_i32_e32 vcc, v72, v52
	v_add3_u32 v100, 0, v24, v72
	v_or_b32_e32 v27, 3, v72
	v_cndmask_b32_e64 v24, v160, 0, vcc
	v_cmp_lt_i32_e32 vcc, v52, v25
	v_or_b32_e32 v26, 4, v72
	v_or_b32_e32 v30, 5, v72
	v_cndmask_b32_e64 v25, v160, 0, vcc
	v_cmp_lt_i32_e32 vcc, v72, v52
	v_or_b32_e32 v31, 7, v72
	v_add_u32_e32 v55, 38, v72
	v_cndmask_b32_e32 v28, 0, v160, vcc
	v_cmp_gt_i32_e32 vcc, v27, v52
	v_or_b32_e32 v27, 6, v72
	v_pack_b32_f16 v24, v24, v28
	v_cndmask_b32_e64 v29, v160, 0, vcc
	v_cmp_gt_i32_e32 vcc, v26, v52
	v_or_b32_e32 v28, 32, v72
	v_pack_b32_f16 v25, v25, v29
	v_cndmask_b32_e64 v26, v160, 0, vcc
	v_cmp_gt_i32_e32 vcc, v30, v52
	v_add_u32_e32 v29, 33, v72
	v_or_b32_e32 v48, 1, v37
	v_cndmask_b32_e64 v30, v160, 0, vcc
	v_cmp_gt_i32_e32 vcc, v27, v52
	v_pack_b32_f16 v26, v26, v30
	v_add_u32_e32 v30, 34, v72
	v_cndmask_b32_e64 v27, v160, 0, vcc
	v_cmp_gt_i32_e32 vcc, v31, v52
	v_lshlrev_b32_e32 v35, 2, v90
	v_readlane_b32 s9, v254, 22
	v_cndmask_b32_e64 v31, v160, 0, vcc
	v_cmp_gt_i32_e32 vcc, v28, v52
	v_pack_b32_f16 v27, v27, v31
	v_add_u32_e32 v31, 36, v72
	v_cndmask_b32_e64 v28, v160, 0, vcc
	v_cmp_gt_i32_e32 vcc, v29, v52
	v_readlane_b32 s0, v255, 37
	v_lshlrev_b32_e32 v45, 4, v37
	v_cndmask_b32_e64 v53, v160, 0, vcc
	v_cmp_gt_i32_e32 vcc, v30, v52
	v_add_u32_e32 v30, 35, v72
	v_lshlrev_b32_e32 v49, 4, v48
	v_cndmask_b32_e64 v29, v160, 0, vcc
	v_cmp_gt_i32_e32 vcc, v30, v52
	v_or_b32_e32 v46, v45, v91
	v_or_b32_e32 v50, v49, v91
	v_cndmask_b32_e64 v54, v160, 0, vcc
	v_cmp_gt_i32_e32 vcc, v31, v52
	v_add_u32_e32 v31, 37, v72
	v_pack_b32_f16 v28, v28, v53
	v_cndmask_b32_e64 v30, v160, 0, vcc
	v_cmp_gt_i32_e32 vcc, v31, v52
	v_add_u32_e32 v101, s0, v44
	v_or_b32_e32 v44, 1, v73
	v_cndmask_b32_e64 v56, v160, 0, vcc
	v_cmp_gt_i32_e32 vcc, v55, v52
	v_add_u32_e32 v55, 39, v72
	v_cmp_le_i32_e64 s[6:7], v37, v41
	v_cndmask_b32_e64 v31, v160, 0, vcc
	v_cmp_gt_i32_e32 vcc, v55, v52
	v_lshlrev_b32_e32 v53, 5, v37
	v_cmp_lt_i32_e64 s[8:9], v37, v41
	v_cndmask_b32_e64 v55, v160, 0, vcc
	v_lshlrev_b32_e32 v41, 5, v48
	v_lshlrev_b32_e32 v37, 6, v37
	v_or_b32_e32 v45, v45, v35
	v_lshlrev_b32_e32 v48, 6, v48
	v_or_b32_e32 v35, v49, v35
	v_readlane_b32 s10, v254, 23
	v_readlane_b32 s11, v254, 24
	v_readlane_b32 s16, v254, 29
	v_readlane_b32 s17, v254, 30
	v_readlane_b32 s18, v254, 31
	v_readlane_b32 s19, v254, 32
	v_readlane_b32 s20, v254, 33
	v_readlane_b32 s21, v254, 34
	v_readlane_b32 s22, v254, 35
	v_readlane_b32 s23, v254, 36
	v_add_u32_e32 v40, s80, v34
	v_add_u32_e32 v43, s0, v34
	v_add_u32_e32 v36, 0, v36
	v_add_u32_e32 v96, 0, v34
	v_mul_u32_u24_e32 v47, 48, v46
	v_mul_u32_u24_e32 v51, 48, v50
	v_pack_b32_f16 v31, v31, v55
	v_pack_b32_f16 v30, v30, v56
	v_pack_b32_f16 v29, v29, v54
	v_mul_u32_u24_e32 v44, 0x90, v44
	v_mul_u32_u24_e32 v103, 0x90, v91
	v_add_u32_e32 v104, v38, v37
	v_mul_u32_u24_e32 v54, 0x90, v45
	v_or_b32_e32 v55, 2, v45
	v_or_b32_e32 v56, 3, v45
	v_add_u32_e32 v105, v38, v48
	v_mul_u32_u24_e32 v38, 0x90, v35
	v_or_b32_e32 v49, 2, v35
	v_or_b32_e32 v57, 3, v35
	v_sub_u32_e32 v115, 0xbf, v32
	v_add_u32_e32 v116, 64, v32
	v_mov_b32_e32 v32, 0
	v_lshl_add_u32 v95, v72, 1, 0
	v_add_u32_e32 v102, 16, v101
	v_mul_u32_u24_e32 v106, 0x90, v46
	v_add_u32_e32 v107, v42, v37
	v_mul_u32_u24_e32 v108, 0x90, v50
	v_add_u32_e32 v109, v42, v48
	v_cmp_gt_i32_e64 s[10:11], v45, v52
	v_cmp_lt_i32_e64 s[12:13], v45, v52
	v_cmp_gt_i32_e64 s[14:15], v55, v52
	v_cmp_gt_i32_e64 s[16:17], v56, v52
	v_cmp_gt_i32_e64 s[18:19], v35, v52
	v_cmp_lt_i32_e64 s[20:21], v35, v52
	v_cmp_gt_i32_e64 s[22:23], v49, v52
	v_cmp_gt_i32_e64 s[24:25], v57, v52
	v_add_u32_e32 v110, v43, v37
	v_add_u32_e32 v111, v43, v48
	s_mov_b32 s26, 0
	v_sub_u32_e32 v112, 0, v91
	v_add_u32_e32 v113, 64, v33
	v_sub_u32_e32 v114, 0xbf, v33
	v_add_u32_e32 v117, v40, v47
	v_add_u32_e32 v118, v39, v54
	v_add_u32_e32 v119, v40, v51
	v_add_u32_e32 v120, v39, v38
	v_lshlrev_b32_e32 v84, 1, v2
	v_add_u32_e32 v121, v78, v44
	v_add_u32_e32 v122, v100, v53
	v_add_u32_e32 v123, v100, v41
	v_add_u32_e32 v124, v36, v34
	v_add_u32_e32 v125, v96, v103
	s_mov_b32 s27, 0
	s_mov_b32 s28, 0
	v_mov_b32_e32 v33, v32
	v_mov_b32_e32 v34, v32
	v_mov_b32_e32 v35, v32
	v_mov_b32_e32 v44, v32
	v_mov_b32_e32 v45, v32
	v_mov_b32_e32 v46, v32
	v_mov_b32_e32 v47, v32
	v_mov_b32_e32 v40, v32
	v_mov_b32_e32 v41, v32
	v_mov_b32_e32 v42, v32
	v_mov_b32_e32 v43, v32
	v_mov_b32_e32 v36, v32
	v_mov_b32_e32 v37, v32
	v_mov_b32_e32 v38, v32
	v_mov_b32_e32 v39, v32
	v_bfe_u32 v244, v238, 6, 2
	v_and_b32_e32 v245, 3, v238
	v_xor_b32_e32 v245, v244, v245
	v_sub_u32_e32 v245, v245, v244
	v_lshlrev_b32_e32 v247, 4, v245
	v_add_u32_e32 v98, v98, v247
	v_add_u32_e32 v99, v99, v247
	v_add_u32_e32 v121, v121, v247
	v_bfe_u32 v245, v238, 4, 2
	v_xor_b32_e32 v246, v245, v244
	v_sub_u32_e32 v246, v246, v245
	v_lshl_add_u32 v124, v246, 4, v124
	v_bfe_u32 v246, v238, 3, 1
	v_xor_b32_e32 v248, v245, v246
	v_xor_b32_e32 v249, 2, v248
	v_sub_u32_e32 v248, v248, v245
	v_sub_u32_e32 v249, v249, v245
	v_lshl_add_u32 v248, v248, 4, v125
	v_lshl_add_u32 v249, v249, 4, v125
	v_and_b32_e32 v246, 7, v238
	v_xor_b32_e32 v244, v245, v246
	v_sub_u32_e32 v244, v244, v245
	v_lshl_add_u32 v107, v244, 4, v107
	v_or_b32_e32 v245, 4, v245
	v_xor_b32_e32 v244, v245, v246
	v_sub_u32_e32 v244, v244, v245
	v_lshl_add_u32 v109, v244, 4, v109
	v_lshlrev_b32_e32 v245, 1, v246
	v_bfe_u32 v246, v238, 3, 3
	v_xor_b32_e32 v244, v245, v246
	v_sub_u32_e32 v244, v244, v245
	v_or_b32_e32 v245, 1, v245
	v_xor_b32_e32 v246, v245, v246
	v_sub_u32_e32 v246, v246, v245
	v_lshl_add_u32 v250, v246, 4, v94
	v_lshl_add_u32 v94, v244, 4, v94
	s_branch .LBB0_901
.LBB0_900:
	s_or_b64 exec, exec, s[0:1]
	s_nop 5
	v_cvt_f16_f32_e32 v2, v52
	v_cvt_f16_f32_e32 v52, v53
	v_cvt_f16_f32_e32 v53, v54
	v_cvt_f16_f32_e32 v54, v55
	v_cndmask_b32_e64 v2, v2, 0, s[18:19]
	v_cndmask_b32_e64 v52, 0, v52, s[20:21]
	v_cndmask_b32_e64 v53, v53, 0, s[22:23]
	v_cndmask_b32_e64 v54, v54, 0, s[24:25]
	v_pack_b32_f16 v53, v53, v54
	v_pack_b32_f16 v52, v2, v52
	ds_write_b64 v123, v[52:53]
	s_waitcnt lgkmcnt(0)
	s_barrier
	ds_read_b128 v[68:71], v124 offset:55296
	ds_read_b128 v[126:129], v124 offset:55360
	ds_read_b128 v[52:55], v125
	s_waitcnt lgkmcnt(0)
	v_mfma_f32_16x16x32_f16 v[48:51], v[68:71], v[52:55], v[48:51]
	ds_read_b128 v[52:55], v125 offset:64
	v_add_u32_e32 v2, 0x1e500, v96
	s_add_i32 s28, s28, 1
	s_waitcnt lgkmcnt(0)
	v_mfma_f32_16x16x32_f16 v[52:55], v[126:129], v[52:55], v[48:51]
	s_nop 2
	ds_read_b128 v[48:51], v125 offset:2304
	s_waitcnt lgkmcnt(0)
	v_mfma_f32_16x16x32_f16 v[48:51], v[68:71], v[48:51], v[56:59]
	s_nop 2
	ds_read_b128 v[56:59], v125 offset:2368
	v_cvt_pk_f16_f32 v55, v54, v55
	v_cvt_pk_f16_f32 v54, v52, v53
	s_waitcnt lgkmcnt(0)
	v_mfma_f32_16x16x32_f16 v[56:59], v[126:129], v[56:59], v[48:51]
	s_nop 2
	ds_read_b128 v[48:51], v125 offset:4608
	s_waitcnt lgkmcnt(0)
	v_mfma_f32_16x16x32_f16 v[48:51], v[68:71], v[48:51], v[60:63]
	s_nop 2
	ds_read_b128 v[60:63], v125 offset:4672
	s_waitcnt lgkmcnt(0)
	v_mfma_f32_16x16x32_f16 v[60:63], v[126:129], v[60:63], v[48:51]
	s_nop 2
	ds_read_b128 v[48:51], v125 offset:6912
	s_waitcnt lgkmcnt(0)
	v_mfma_f32_16x16x32_f16 v[48:51], v[68:71], v[48:51], v[64:67]
	s_nop 2
	ds_read_b128 v[64:67], v125 offset:6976
	s_waitcnt lgkmcnt(0)
	v_mfma_f32_16x16x32_f16 v[48:51], v[126:129], v[64:67], v[48:51]
	ds_read_b128 v[64:67], v2
	s_waitcnt lgkmcnt(0)
	v_pk_mul_f32 v[44:45], v[44:45], v[64:65]
	v_pk_mul_f32 v[46:47], v[46:47], v[66:67]
	ds_read_b128 v[64:67], v248 offset:46080
	s_nop 2
	v_cvt_pk_f16_f32 v51, v50, v51
	s_waitcnt lgkmcnt(0)
	v_mfma_f32_16x16x32_f16 v[44:47], v[64:67], v[68:71], v[44:47]
	ds_read_b128 v[64:67], v248 offset:46144
	v_cvt_pk_f16_f32 v50, v48, v49
	s_waitcnt lgkmcnt(0)
	v_mfma_f32_16x16x32_f16 v[44:47], v[64:67], v[126:129], v[44:47]
	ds_read_b128 v[64:67], v2 offset:64
	s_waitcnt lgkmcnt(0)
	v_pk_mul_f32 v[32:33], v[32:33], v[64:65]
	v_pk_mul_f32 v[34:35], v[34:35], v[66:67]
	ds_read_b128 v[64:67], v249 offset:48384
	s_waitcnt lgkmcnt(0)
	v_mfma_f32_16x16x32_f16 v[32:35], v[64:67], v[68:71], v[32:35]
	ds_read_b128 v[64:67], v249 offset:48448
	s_waitcnt lgkmcnt(0)
	v_mfma_f32_16x16x32_f16 v[32:35], v[64:67], v[126:129], v[32:35]
	ds_read_b128 v[64:67], v2 offset:128
	s_waitcnt lgkmcnt(0)
	v_pk_mul_f32 v[40:41], v[40:41], v[64:65]
	v_pk_mul_f32 v[42:43], v[42:43], v[66:67]
	ds_read_b128 v[64:67], v248 offset:50688
	s_waitcnt lgkmcnt(0)
	v_mfma_f32_16x16x32_f16 v[40:43], v[64:67], v[68:71], v[40:43]
	ds_read_b128 v[64:67], v248 offset:50752
	s_waitcnt lgkmcnt(0)
	v_mfma_f32_16x16x32_f16 v[40:43], v[64:67], v[126:129], v[40:43]
	ds_read_b128 v[64:67], v2 offset:192
	v_add_u32_e32 v2, s26, v91
	s_add_i32 s26, s26, 64
	s_waitcnt lgkmcnt(0)
	v_pk_mul_f32 v[36:37], v[36:37], v[64:65]
	v_pk_mul_f32 v[38:39], v[38:39], v[66:67]
	ds_read_b128 v[64:67], v249 offset:52992
	s_waitcnt lgkmcnt(0)
	v_mfma_f32_16x16x32_f16 v[36:39], v[64:67], v[68:71], v[36:39]
	ds_read_b128 v[64:67], v249 offset:53056
	s_waitcnt lgkmcnt(0)
	v_mfma_f32_16x16x32_f16 v[36:39], v[64:67], v[126:129], v[36:39]
	v_add_u32_e32 v64, s27, v112
	v_add_u32_e32 v65, 0xff, v64
	v_cndmask_b32_e64 v65, v65, v2, s[2:3]
	v_add_u32_e32 v52, v65, v89
	v_mad_i64_i32 v[52:53], s[0:1], v52, s88, v[82:83]
	global_store_dwordx2 v[52:53], v[54:55], off
	v_add_u32_e32 v52, 16, v2
	v_add_u32_e32 v53, 0xef, v64
	v_cndmask_b32_e64 v54, v53, v52, s[2:3]
	v_add_u32_e32 v54, v54, v89
	v_cvt_pk_f16_f32 v53, v58, v59
	v_cvt_pk_f16_f32 v52, v56, v57
	v_mad_i64_i32 v[54:55], s[0:1], v54, s88, v[82:83]
	global_store_dwordx2 v[54:55], v[52:53], off
	v_add_u32_e32 v52, 32, v2
	v_add_u32_e32 v53, 0xdf, v64
	v_cndmask_b32_e64 v54, v53, v52, s[2:3]
	v_add_u32_e32 v54, v54, v89
	v_cvt_pk_f16_f32 v53, v62, v63
	v_cvt_pk_f16_f32 v52, v60, v61
	v_mad_i64_i32 v[54:55], s[0:1], v54, s88, v[82:83]
	global_store_dwordx2 v[54:55], v[52:53], off
	v_add_u32_e32 v2, 48, v2
	v_add_u32_e32 v52, 0xcf, v64
	v_cndmask_b32_e64 v2, v52, v2, s[2:3]
	v_add_u32_e32 v2, v2, v89
	s_sub_i32 s27, s27, 64
	v_mad_i64_i32 v[48:49], s[0:1], v2, s88, v[82:83]
	s_cmpk_lg_i32 s27, 0xff00
	global_store_dwordx2 v[48:49], v[50:51], off
	s_cbranch_scc0 .LBB0_1058

.LBB0_913:
	s_or_b64 exec, exec, s[0:1]
	s_waitcnt lgkmcnt(0)
	s_barrier
	ds_read_b128 v[48:51], v92
	ds_read_b128 v[52:55], v92 offset:9216
	ds_read_b128 v[60:63], v94
	ds_read_b128 v[56:59], v250 offset:16
	ds_read_b128 v[68:71], v101
	v_add_u32_e32 v81, v95, v103
	s_waitcnt lgkmcnt(3)
	v_cvt_f32_f16_sdwa v67, v52 dst_sel:DWORD dst_unused:UNUSED_PAD src0_sel:WORD_1
	s_waitcnt lgkmcnt(2)
	v_mul_f32_e32 v2, 0x3fb8aa3b, v60
	v_exp_f32_e32 v60, v2
	v_mul_f32_e32 v2, 0x3fb8aa3b, v61
	v_exp_f32_e32 v61, v2
	v_cvt_f32_f16_e32 v66, v52
	v_rcp_f32_e32 v64, v60
	v_add3_u32 v52, v78, v97, v247
	v_rcp_f32_e32 v65, v61
	v_cvt_f32_f16_sdwa v127, v54 dst_sel:DWORD dst_unused:UNUSED_PAD src0_sel:WORD_1
	v_cvt_f32_f16_e32 v126, v54
	v_pk_mul_f32 v[66:67], v[64:65], v[66:67]
	v_cvt_f32_f16_sdwa v65, v48 dst_sel:DWORD dst_unused:UNUSED_PAD src0_sel:WORD_1
	v_cvt_f32_f16_e32 v64, v48
	s_waitcnt lgkmcnt(0)
	v_fma_mixlo_f16 v2, v68, v66, 0
	ds_write_b16 v52, v2 offset:46080
	v_fma_mixlo_f16 v2, v69, v67, 0
	v_pk_mul_f32 v[64:65], v[64:65], s[72:73] op_sel_hi:[1,0]
	ds_write_b16 v121, v2 offset:46080
	v_mul_f32_e32 v2, 0x3fb8aa3b, v62
	v_pk_mul_f32 v[64:65], v[64:65], v[60:61]
	v_exp_f32_e32 v60, v2
	v_mul_f32_e32 v2, 0x3fb8aa3b, v63
	v_exp_f32_e32 v61, v2
	v_cvt_f32_f16_sdwa v69, v53 dst_sel:DWORD dst_unused:UNUSED_PAD src0_sel:WORD_1
	v_rcp_f32_e32 v62, v60
	v_cvt_f32_f16_e32 v68, v53
	v_rcp_f32_e32 v63, v61
	v_cvt_f32_f16_sdwa v53, v49 dst_sel:DWORD dst_unused:UNUSED_PAD src0_sel:WORD_1
	v_cvt_f32_f16_e32 v52, v49
	v_cvt_pk_f16_f32 v48, v64, v65
	v_pk_mul_f32 v[68:69], v[62:63], v[68:69]
	v_pk_mul_f32 v[52:53], v[52:53], s[72:73] op_sel_hi:[1,0]
	v_fma_mixlo_f16 v2, v70, v68, 0
	ds_write_b16 v121, v2 offset:46224
	v_fma_mixlo_f16 v2, v71, v69, 0
	ds_write_b16 v121, v2 offset:46368
	v_mul_f32_e32 v2, 0x3fb8aa3b, v56
	v_exp_f32_e32 v56, v2
	v_mul_f32_e32 v2, 0x3fb8aa3b, v57
	v_exp_f32_e32 v57, v2
	v_pk_mul_f32 v[52:53], v[52:53], v[60:61]
	v_rcp_f32_e32 v70, v56
	ds_read_b128 v[60:63], v102
	v_rcp_f32_e32 v71, v57
	v_cvt_pk_f16_f32 v49, v52, v53
	v_pk_mul_f32 v[70:71], v[70:71], v[126:127]
	s_waitcnt lgkmcnt(0)
	v_fma_mixlo_f16 v2, v60, v70, 0
	ds_write_b16 v121, v2 offset:46512
	v_fma_mixlo_f16 v2, v61, v71, 0
	ds_write_b16 v121, v2 offset:46656
	v_mul_f32_e32 v2, 0x3fb8aa3b, v58
	v_cvt_f32_f16_sdwa v127, v50 dst_sel:DWORD dst_unused:UNUSED_PAD src0_sel:WORD_1
	v_cvt_f32_f16_e32 v126, v50
	v_exp_f32_e32 v58, v2
	v_mul_f32_e32 v2, 0x3fb8aa3b, v59
	v_exp_f32_e32 v59, v2
	v_pk_mul_f32 v[126:127], v[126:127], s[72:73] op_sel_hi:[1,0]
	v_cvt_f32_f16_sdwa v61, v55 dst_sel:DWORD dst_unused:UNUSED_PAD src0_sel:WORD_1
	v_pk_mul_f32 v[126:127], v[126:127], v[56:57]
	v_rcp_f32_e32 v56, v58
	v_rcp_f32_e32 v57, v59
	v_cvt_f32_f16_e32 v60, v55
	v_bfe_u32 v55, v71, 16, 1
	v_add3_u32 v55, v71, v55, s34
	v_cvt_pk_f16_f32 v50, v126, v127
	v_pk_mul_f32 v[128:129], v[56:57], v[60:61]
	v_bfe_u32 v56, v70, 16, 1
	v_fma_mixlo_f16 v2, v62, v128, 0
	ds_write_b16 v121, v2 offset:46800
	v_bfe_u32 v2, v129, 16, 1
	v_bfe_u32 v54, v128, 16, 1
	v_bfe_u32 v57, v69, 16, 1
	v_bfe_u32 v60, v68, 16, 1
	v_bfe_u32 v61, v67, 16, 1
	v_bfe_u32 v62, v66, 16, 1
	v_add3_u32 v62, v66, v62, s34
	v_add3_u32 v61, v67, v61, s34
	v_add3_u32 v60, v68, v60, s34
	v_add3_u32 v66, v69, v57, s34
	v_add3_u32 v56, v70, v56, s34
	v_add3_u32 v54, v128, v54, s34
	v_add3_u32 v2, v129, v2, s34
	v_perm_b32 v57, v2, v54, s35
	v_perm_b32 v56, v55, v56, s35
	v_perm_b32 v55, v66, v60, s35
	v_perm_b32 v54, v61, v62, s35
	v_cvt_f32_f16_sdwa v61, v51 dst_sel:DWORD dst_unused:UNUSED_PAD src0_sel:WORD_1
	v_cvt_f32_f16_e32 v60, v51
	v_bfe_u32 v62, v126, 16, 1
	v_bfe_u32 v66, v53, 16, 1
	v_bfe_u32 v67, v52, 16, 1
	v_pk_mul_f32 v[60:61], v[60:61], s[72:73] op_sel_hi:[1,0]
	v_bfe_u32 v68, v65, 16, 1
	v_pk_mul_f32 v[58:59], v[60:61], v[58:59]
	v_bfe_u32 v61, v127, 16, 1
	v_bfe_u32 v2, v59, 16, 1
	v_bfe_u32 v60, v58, 16, 1
	v_cvt_pk_f16_f32 v51, v58, v59
	v_bfe_u32 v69, v64, 16, 1
	v_add3_u32 v58, v58, v60, s34
	v_add3_u32 v2, v59, v2, s34
	v_add3_u32 v64, v64, v69, s34
	v_add3_u32 v65, v65, v68, s34
	v_add3_u32 v52, v52, v67, s34
	v_add3_u32 v53, v53, v66, s34
	v_add3_u32 v62, v126, v62, s34
	v_add3_u32 v66, v127, v61, s34
	v_perm_b32 v61, v2, v58, s35
	v_fma_mixlo_f16 v2, v63, v129, 0
	v_perm_b32 v60, v66, v62, s35
	v_perm_b32 v59, v53, v52, s35
	v_perm_b32 v58, v65, v64, s35
	ds_write_b16 v121, v2 offset:46944
	ds_write_b128 v92, v[58:61] offset:18432
	ds_write_b128 v92, v[54:57] offset:27648
	ds_write_b128 v92, v[48:51] offset:36864
	v_add_u32_e32 v2, v79, v72
	s_waitcnt lgkmcnt(0)
	s_barrier
	ds_read_b128 v[48:51], v2
	ds_read_b128 v[52:55], v81 offset:36864
	ds_read_b128 v[56:59], v81 offset:39168
	ds_read_b128 v[60:63], v81 offset:41472
	ds_read_b128 v[64:67], v81 offset:43776
	s_waitcnt lgkmcnt(3)
	v_mfma_f32_16x16x32_f16 v[52:55], v[48:51], v[52:55], 0
	s_waitcnt lgkmcnt(2)
	v_mfma_f32_16x16x32_f16 v[56:59], v[48:51], v[56:59], 0
	s_waitcnt lgkmcnt(1)
	v_mfma_f32_16x16x32_f16 v[60:63], v[48:51], v[60:63], 0
	s_waitcnt lgkmcnt(0)
	v_mfma_f32_16x16x32_f16 v[64:67], v[48:51], v[64:67], 0
	ds_read_b128 v[68:71], v2 offset:64
	ds_read_b128 v[48:51], v81 offset:36928
	v_add_u32_e32 v2, v100, v72
	s_waitcnt lgkmcnt(0)
	v_mfma_f32_16x16x32_f16 v[48:51], v[68:71], v[48:51], v[52:55]
	s_nop 2
	ds_read_b128 v[52:55], v81 offset:39232
	s_waitcnt lgkmcnt(0)
	v_mfma_f32_16x16x32_f16 v[56:59], v[68:71], v[52:55], v[56:59]
	ds_read_b128 v[52:55], v81 offset:41536
	s_waitcnt lgkmcnt(0)
	v_mfma_f32_16x16x32_f16 v[60:63], v[68:71], v[52:55], v[60:63]
	ds_read_b128 v[52:55], v81 offset:43840
	s_waitcnt lgkmcnt(0)
	v_mfma_f32_16x16x32_f16 v[64:67], v[68:71], v[52:55], v[64:67]
	v_mov_b32_e32 v52, 0
	v_mov_b32_e32 v68, 0
	v_mov_b32_e32 v69, 0
	v_mov_b32_e32 v70, 0
	v_mov_b32_e32 v71, 0
	s_and_saveexec_b64 s[0:1], s[6:7]
	s_cbranch_execz .LBB0_915
	v_add_u32_e32 v53, v95, v106
	ds_read_b128 v[68:71], v2 offset:18432
	ds_read_b128 v[126:129], v53 offset:27648
	s_waitcnt lgkmcnt(0)
	v_mfma_f32_16x16x32_bf16 v[68:71], v[126:129], v[68:71], 0
	ds_read_b128 v[126:129], v2 offset:18496
	ds_read_b128 v[130:133], v53 offset:27712
	s_waitcnt lgkmcnt(0)
	v_mfma_f32_16x16x32_bf16 v[68:71], v[130:133], v[126:129], v[68:71]

.LBB0_993:
	s_or_b64 exec, exec, s[0:1]
	v_readlane_b32 s8, v254, 21
	v_readlane_b32 s13, v254, 26
	v_readlane_b32 s15, v254, 28
	v_lshlrev_b32_e32 v53, 2, v46
	v_readlane_b32 s12, v254, 25
	v_readlane_b32 s14, v254, 27
	v_mov_b32_e32 v45, s15
	v_mov_b32_e32 v46, s13
	v_cndmask_b32_e64 v55, v45, v46, s[2:3]
	v_mov_b32_e32 v45, s14
	v_mov_b32_e32 v46, s12
	v_cndmask_b32_e64 v54, v45, v46, s[2:3]
	v_mul_lo_u32 v45, v82, s89
	v_add_u32_e32 v46, 0, v45
	s_movk_i32 s0, 0xff72
	v_mad_u64_u32 v[72:73], s[0:1], v82, s0, v[46:47]
	v_mul_lo_u32 v43, v43, s89
	v_readlane_b32 s0, v255, 43
	v_lshlrev_b32_e32 v1, 3, v47
	v_lshlrev_b32_e32 v41, 1, v41
	v_add3_u32 v73, s0, v43, v0
	s_add_i32 s0, 0, 0x1e400
	v_and_b32_e32 v56, 2, v41
	v_add_u32_e32 v57, s0, v52
	v_lshlrev_b32_e32 v41, 1, v51
	v_lshlrev_b32_e32 v45, 1, v80
	v_readlane_b32 s0, v255, 33
	v_ashrrev_i32_e32 v59, 7, v40
	v_readlane_b32 s6, v255, 34
	v_lshlrev_b32_e32 v74, 1, v2
	v_xor_b32_e32 v2, 16, v1
	v_readlane_b32 s9, v254, 22
	v_add3_u32 v51, s0, v41, v45
	v_lshlrev_b32_e32 v41, 4, v59
	v_lshl_add_u32 v45, v59, 12, s6
	v_lshlrev_b32_e32 v60, 8, v80
	v_mov_b32_e32 v75, v3
	v_lshl_add_u32 v88, v2, 1, v46
	v_and_b32_e32 v2, 2, v40
	v_mul_u32_u24_e32 v89, 0x480, v47
	v_add_u32_e32 v84, s0, v52
	v_add3_u32 v60, v45, v60, v52
	v_cmp_eq_u32_e32 vcc, 3, v59
	v_cmp_eq_u32_e64 s[0:1], 15, v80
	v_lshlrev_b32_e32 v45, 8, v82
	v_lshlrev_b32_e32 v62, 2, v1
	v_add_u32_e32 v63, 0, v43
	v_lshl_add_u64 v[54:55], v[54:55], 0, v[74:75]
	v_ashrrev_i32_e32 v43, 31, v42
	v_cmp_eq_u32_e64 s[8:9], 0, v2
	v_lshlrev_b32_e32 v2, 1, v89
	v_lshlrev_b32_e32 v40, 1, v82
	v_or_b32_e32 v69, v41, v80
	s_and_b64 s[68:69], vcc, s[0:1]
	v_add3_u32 v85, s6, v45, v62
	v_lshl_add_u64 v[42:43], v[42:43], 1, v[54:55]
	v_mov_b32_e32 v45, v3
	v_add3_u32 v91, 0, v2, v40
	v_or_b32_e32 v40, 2, v0
	v_cmp_gt_i32_e32 vcc, v0, v69
	v_lshl_add_u64 v[76:77], v[42:43], 0, v[44:45]
	v_mul_lo_u32 v41, v69, s89
	v_cndmask_b32_e64 v44, v160, 0, vcc
	v_cmp_lt_i32_e32 vcc, v69, v40
	v_or_b32_e32 v42, 3, v0
	v_add3_u32 v92, 0, v41, v0
	v_cndmask_b32_e64 v40, v160, 0, vcc
	v_cmp_lt_i32_e32 vcc, v0, v69
	v_or_b32_e32 v41, 4, v0
	v_lshl_add_u32 v83, v1, 1, v46
	v_cndmask_b32_e32 v45, 0, v160, vcc
	v_cmp_gt_i32_e32 vcc, v42, v69
	v_or_b32_e32 v43, 5, v0
	v_or_b32_e32 v42, 6, v0
	v_cndmask_b32_e64 v46, v160, 0, vcc
	v_cmp_gt_i32_e32 vcc, v41, v69
	v_cmp_gt_u32_e64 s[6:7], 4, v47
	v_add_u32_e32 v79, 38, v0
	v_cndmask_b32_e64 v41, v160, 0, vcc
	v_cmp_gt_i32_e32 vcc, v43, v69
	v_or_b32_e32 v43, 7, v0
	v_or_b32_e32 v65, 1, v56
	v_cndmask_b32_e64 v47, v160, 0, vcc
	v_cmp_gt_i32_e32 vcc, v42, v69
	v_readlane_b32 s10, v254, 23
	v_readlane_b32 s11, v254, 24
	v_cndmask_b32_e64 v42, v160, 0, vcc
	v_cmp_gt_i32_e32 vcc, v43, v69
	v_readlane_b32 s0, v255, 37
	v_add_u32_e32 v90, v72, v2
	v_cndmask_b32_e64 v43, v160, 0, vcc
	v_pack_b32_f16 v43, v42, v43
	v_pack_b32_f16 v42, v41, v47
	v_pack_b32_f16 v41, v40, v46
	v_pack_b32_f16 v40, v44, v45
	v_or_b32_e32 v44, 32, v0
	v_cmp_gt_i32_e32 vcc, v44, v69
	v_add_u32_e32 v45, 33, v0
	v_add_u32_e32 v46, 34, v0
	v_cndmask_b32_e64 v44, v160, 0, vcc
	v_cmp_gt_i32_e32 vcc, v45, v69
	v_add_u32_e32 v47, 36, v0
	v_lshlrev_b32_e32 v2, 4, v56
	v_cndmask_b32_e64 v75, v160, 0, vcc
	v_cmp_gt_i32_e32 vcc, v46, v69
	v_add_u32_e32 v46, 35, v0
	v_lshlrev_b32_e32 v66, 4, v65
	v_cndmask_b32_e64 v45, v160, 0, vcc
	v_cmp_gt_i32_e32 vcc, v46, v69
	v_or_b32_e32 v55, v2, v80
	v_or_b32_e32 v67, v66, v80
	v_cndmask_b32_e64 v78, v160, 0, vcc
	v_cmp_gt_i32_e32 vcc, v47, v69
	v_add_u32_e32 v47, 37, v0
	v_pack_b32_f16 v44, v44, v75
	v_cndmask_b32_e64 v46, v160, 0, vcc
	v_cmp_gt_i32_e32 vcc, v47, v69
	v_cmp_le_i32_e64 s[10:11], v56, v59
	v_lshlrev_b32_e32 v75, 5, v56
	v_cndmask_b32_e64 v93, v160, 0, vcc
	v_cmp_gt_i32_e32 vcc, v79, v69
	v_add_u32_e32 v79, 39, v0
	v_pack_b32_f16 v46, v46, v93
	v_cndmask_b32_e64 v47, v160, 0, vcc
	v_cmp_gt_i32_e32 vcc, v79, v69
	v_add_u32_e32 v93, s0, v62
	v_or_b32_e32 v62, 1, v1
	v_cndmask_b32_e64 v79, v160, 0, vcc
	v_cmp_lt_i32_e64 s[12:13], v56, v59
	v_lshlrev_b32_e32 v59, 5, v65
	v_lshlrev_b32_e32 v56, 6, v56
	v_or_b32_e32 v2, v2, v53
	v_lshlrev_b32_e32 v65, 6, v65
	v_or_b32_e32 v53, v66, v53
	v_readlane_b32 s16, v254, 29
	v_readlane_b32 s17, v254, 30
	v_readlane_b32 s18, v254, 31
	v_readlane_b32 s19, v254, 32
	v_readlane_b32 s20, v254, 33
	v_readlane_b32 s21, v254, 34
	v_readlane_b32 s22, v254, 35
	v_readlane_b32 s23, v254, 36
	v_add_u32_e32 v58, s80, v52
	v_add_u32_e32 v61, s0, v52
	v_add_u32_e32 v87, 0, v52
	v_and_b32_e32 v54, 8, v1
	v_mul_u32_u24_e32 v64, 48, v55
	v_mul_u32_u24_e32 v68, 48, v67
	v_pack_b32_f16 v47, v47, v79
	v_pack_b32_f16 v45, v45, v78
	v_mul_u32_u24_e32 v62, 0x90, v62
	v_mul_u32_u24_e32 v95, 0x90, v80
	v_add_u32_e32 v96, v57, v56
	v_mul_u32_u24_e32 v78, 0x90, v2
	v_or_b32_e32 v79, 2, v2
	v_or_b32_e32 v102, 3, v2
	v_add_u32_e32 v97, v57, v65
	v_mul_u32_u24_e32 v57, 0x90, v53
	v_or_b32_e32 v66, 2, v53
	v_or_b32_e32 v103, 3, v53
	s_mov_b32 s31, s80
	v_lshl_add_u32 v86, v0, 1, 0
	s_mov_b32 s80, 0
	v_add_u32_e32 v94, 16, v93
	v_mul_u32_u24_e32 v98, 0x90, v55
	v_add_u32_e32 v99, v60, v56
	v_mul_u32_u24_e32 v100, 0x90, v67
	v_add_u32_e32 v101, v60, v65
	v_cmp_gt_i32_e64 s[14:15], v2, v69
	v_cmp_lt_i32_e64 s[16:17], v2, v69
	v_cmp_gt_i32_e64 s[18:19], v79, v69
	v_cmp_gt_i32_e64 s[20:21], v102, v69
	v_cmp_gt_i32_e64 s[22:23], v53, v69
	v_cmp_lt_i32_e64 s[24:25], v53, v69
	v_cmp_gt_i32_e64 s[26:27], v66, v69
	v_cmp_gt_i32_e64 s[28:29], v103, v69
	v_add_u32_e32 v102, v61, v56
	v_add_u32_e32 v103, v61, v65
	v_sub_u32_e32 v104, 0, v80
	v_sub_u32_e32 v105, 0, v82
	v_add_u32_e32 v106, 64, v49
	v_sub_u32_e32 v107, 0x7bf, v49
	v_add_u32_e32 v108, v58, v64
	v_add_u32_e32 v109, v51, v78
	v_add_u32_e32 v110, v58, v68
	v_add_u32_e32 v111, v51, v57
	v_lshlrev_b32_e32 v2, 1, v48
	v_lshlrev_b32_e32 v78, 1, v50
	v_lshlrev_b32_e32 v112, 2, v54
	v_add_u32_e32 v113, v72, v62
	v_add_u32_e32 v114, v92, v75
	v_add_u32_e32 v115, v92, v59
	v_add_u32_e32 v116, v63, v52
	v_add_u32_e32 v117, v87, v95
	s_mov_b32 s96, 0
	s_mov_b32 s30, 0
	v_bfe_u32 v244, v238, 6, 2
	v_and_b32_e32 v245, 3, v238
	v_xor_b32_e32 v245, v244, v245
	v_sub_u32_e32 v245, v245, v244
	v_lshlrev_b32_e32 v247, 4, v245
	v_add_u32_e32 v90, v90, v247
	v_add_u32_e32 v91, v91, v247
	v_add_u32_e32 v113, v113, v247
	v_bfe_u32 v245, v238, 4, 2
	v_xor_b32_e32 v246, v245, v244
	v_sub_u32_e32 v246, v246, v245
	v_lshl_add_u32 v116, v246, 4, v116
	v_bfe_u32 v246, v238, 3, 1
	v_xor_b32_e32 v248, v245, v246
	v_xor_b32_e32 v249, 2, v248
	v_sub_u32_e32 v248, v248, v245
	v_sub_u32_e32 v249, v249, v245
	v_lshl_add_u32 v248, v248, 4, v117
	v_lshl_add_u32 v249, v249, 4, v117
	v_and_b32_e32 v246, 7, v238
	v_xor_b32_e32 v244, v245, v246
	v_sub_u32_e32 v244, v244, v245
	v_lshl_add_u32 v99, v244, 4, v99
	v_or_b32_e32 v245, 4, v245
	v_xor_b32_e32 v244, v245, v246
	v_sub_u32_e32 v244, v244, v245
	v_lshl_add_u32 v101, v244, 4, v101
	v_lshlrev_b32_e32 v245, 1, v246
	v_bfe_u32 v246, v238, 3, 3
	v_xor_b32_e32 v244, v245, v246
	v_sub_u32_e32 v244, v244, v245
	v_or_b32_e32 v245, 1, v245
	v_xor_b32_e32 v246, v245, v246
	v_sub_u32_e32 v246, v246, v245
	v_lshl_add_u32 v250, v246, 4, v85
	v_lshl_add_u32 v85, v244, 4, v85
	s_branch .LBB0_995
.LBB0_994:
	s_or_b64 exec, exec, s[0:1]
	s_nop 5
	v_cvt_f16_f32_e32 v65, v65
	v_cvt_f16_f32_e32 v64, v64
	s_add_i32 s30, s30, 1
	v_cndmask_b32_e64 v68, 0, v65, s[24:25]
	v_cvt_f16_f32_e32 v65, v66
	v_cvt_f16_f32_e32 v66, v67
	v_cndmask_b32_e64 v64, v64, 0, s[22:23]
	v_pack_b32_f16 v64, v64, v68
	v_cndmask_b32_e64 v65, v65, 0, s[26:27]
	v_cndmask_b32_e64 v66, v66, 0, s[28:29]
	v_pack_b32_f16 v65, v65, v66
	ds_write_b64 v115, v[64:65]
	s_waitcnt lgkmcnt(0)
	s_barrier
	ds_read_b128 v[64:67], v116 offset:55296
	ds_read_b128 v[118:121], v116 offset:55360
	ds_read_b128 v[122:125], v117
	s_waitcnt lgkmcnt(0)
	v_mfma_f32_16x16x32_f16 v[52:55], v[64:67], v[122:125], v[52:55]
	ds_read_b128 v[122:125], v117 offset:64
	v_add_u32_e32 v68, 0x1e500, v87
	s_waitcnt lgkmcnt(0)
	v_mfma_f32_16x16x32_f16 v[52:55], v[118:121], v[122:125], v[52:55]
	ds_read_b128 v[122:125], v117 offset:2304
	s_waitcnt lgkmcnt(0)
	v_mfma_f32_16x16x32_f16 v[56:59], v[64:67], v[122:125], v[56:59]
	ds_read_b128 v[122:125], v117 offset:2368
	s_nop 3
	v_cvt_pk_f16_f32 v55, v54, v55
	v_cvt_pk_f16_f32 v54, v52, v53
	s_waitcnt lgkmcnt(0)
	v_mfma_f32_16x16x32_f16 v[56:59], v[118:121], v[122:125], v[56:59]
	ds_read_b128 v[122:125], v117 offset:4608
	s_waitcnt lgkmcnt(0)
	v_mfma_f32_16x16x32_f16 v[60:63], v[64:67], v[122:125], v[60:63]
	ds_read_b128 v[122:125], v117 offset:4672
	s_waitcnt lgkmcnt(0)
	v_mfma_f32_16x16x32_f16 v[60:63], v[118:121], v[122:125], v[60:63]
	ds_read_b128 v[122:125], v117 offset:6912
	s_waitcnt lgkmcnt(0)
	v_mfma_f32_16x16x32_f16 v[48:51], v[64:67], v[122:125], v[48:51]
	ds_read_b128 v[122:125], v117 offset:6976
	s_waitcnt lgkmcnt(0)
	v_mfma_f32_16x16x32_f16 v[48:51], v[118:121], v[122:125], v[48:51]
	ds_read_b128 v[122:125], v68
	s_waitcnt lgkmcnt(0)
	v_pk_mul_f32 v[8:9], v[8:9], v[122:123]
	v_pk_mul_f32 v[10:11], v[10:11], v[124:125]
	ds_read_b128 v[122:125], v248 offset:46080
	s_nop 2
	v_cvt_pk_f16_f32 v51, v50, v51
	s_waitcnt lgkmcnt(0)
	v_mfma_f32_16x16x32_f16 v[8:11], v[122:125], v[64:67], v[8:11]
	ds_read_b128 v[122:125], v248 offset:46144
	v_cvt_pk_f16_f32 v50, v48, v49
	s_waitcnt lgkmcnt(0)
	v_mfma_f32_16x16x32_f16 v[8:11], v[122:125], v[118:121], v[8:11]
	ds_read_b128 v[122:125], v68 offset:64
	s_waitcnt lgkmcnt(0)
	v_pk_mul_f32 v[4:5], v[4:5], v[122:123]
	v_pk_mul_f32 v[6:7], v[6:7], v[124:125]
	ds_read_b128 v[122:125], v249 offset:48384
	s_waitcnt lgkmcnt(0)
	v_mfma_f32_16x16x32_f16 v[4:7], v[122:125], v[64:67], v[4:7]
	ds_read_b128 v[122:125], v249 offset:48448
	s_waitcnt lgkmcnt(0)
	v_mfma_f32_16x16x32_f16 v[4:7], v[122:125], v[118:121], v[4:7]
	ds_read_b128 v[122:125], v68 offset:128
	s_waitcnt lgkmcnt(0)
	v_pk_mul_f32 v[16:17], v[16:17], v[122:123]
	v_pk_mul_f32 v[18:19], v[18:19], v[124:125]
	ds_read_b128 v[122:125], v248 offset:50688
	s_waitcnt lgkmcnt(0)
	v_mfma_f32_16x16x32_f16 v[16:19], v[122:125], v[64:67], v[16:19]
	ds_read_b128 v[122:125], v248 offset:50752
	s_waitcnt lgkmcnt(0)
	v_mfma_f32_16x16x32_f16 v[16:19], v[122:125], v[118:121], v[16:19]
	ds_read_b128 v[122:125], v68 offset:192
	s_waitcnt lgkmcnt(0)
	v_pk_mul_f32 v[12:13], v[12:13], v[122:123]
	v_pk_mul_f32 v[14:15], v[14:15], v[124:125]
	ds_read_b128 v[122:125], v249 offset:52992
	s_waitcnt lgkmcnt(0)
	v_mfma_f32_16x16x32_f16 v[12:15], v[122:125], v[64:67], v[12:15]
	ds_read_b128 v[64:67], v249 offset:53056
	s_waitcnt lgkmcnt(0)
	v_mfma_f32_16x16x32_f16 v[12:15], v[64:67], v[118:121], v[12:15]
	v_add_u32_e32 v65, s96, v104
	v_add_u32_e32 v64, s80, v80
	v_add_u32_e32 v66, 0x7ff, v65
	v_cndmask_b32_e64 v66, v66, v64, s[2:3]
	v_add_u32_e32 v52, v66, v81
	v_mad_i64_i32 v[52:53], s[0:1], v52, s88, v[76:77]
	global_store_dwordx2 v[52:53], v[54:55], off
	v_add_u32_e32 v52, 16, v64
	v_add_u32_e32 v53, 0x7ef, v65
	v_cndmask_b32_e64 v54, v53, v52, s[2:3]
	v_add_u32_e32 v54, v54, v81
	v_cvt_pk_f16_f32 v53, v58, v59
	v_cvt_pk_f16_f32 v52, v56, v57
	v_mad_i64_i32 v[54:55], s[0:1], v54, s88, v[76:77]
	global_store_dwordx2 v[54:55], v[52:53], off
	v_add_u32_e32 v52, 32, v64
	v_add_u32_e32 v53, 0x7df, v65
	v_cndmask_b32_e64 v54, v53, v52, s[2:3]
	v_add_u32_e32 v54, v54, v81
	v_cvt_pk_f16_f32 v53, v62, v63
	v_cvt_pk_f16_f32 v52, v60, v61
	v_mad_i64_i32 v[54:55], s[0:1], v54, s88, v[76:77]
	global_store_dwordx2 v[54:55], v[52:53], off
	v_add_u32_e32 v52, 48, v64
	v_add_u32_e32 v53, 0x7cf, v65
	v_cndmask_b32_e64 v52, v53, v52, s[2:3]
	v_add_u32_e32 v48, v52, v81
	s_sub_i32 s96, s96, 64
	s_add_i32 s80, s80, 64
	v_mad_i64_i32 v[48:49], s[0:1], v48, s88, v[76:77]
	s_cmpk_lg_i32 s96, 0xf800
	global_store_dwordx2 v[48:49], v[50:51], off
	s_cbranch_scc0 .LBB0_1011

.LBB0_1007:
	s_or_b64 exec, exec, s[0:1]
	v_add_u32_e32 v57, s80, v82
	v_add_u32_e32 v56, 0x7ff, v56
	v_cndmask_b32_e64 v56, v56, v57, s[2:3]
	s_waitcnt lgkmcnt(0)
	s_barrier
	ds_read_b128 v[58:61], v83
	ds_read_b128 v[48:51], v83 offset:9216
	ds_read_b128 v[62:65], v88
	ds_read_b128 v[52:55], v88 offset:9216
	v_lshrrev_b32_e32 v57, 6, v56
	v_and_b32_e32 v56, 63, v56
	v_cndmask_b32_e64 v56, v56, v57, s[6:7]
	v_lshl_or_b32 v57, v56, 6, v112
	ds_read_b128 v[66:69], v85
	ds_read_b128 v[118:121], v250 offset:16
	v_add_u32_e32 v75, s81, v57
	s_add_i32 s0, 0, 0x1f600
	v_add_u32_e32 v79, s0, v57
	ds_read_b128 v[122:125], v75
	ds_read_b128 v[126:129], v79
	s_waitcnt lgkmcnt(5)
	v_cvt_f32_f16_sdwa v137, v62 dst_sel:DWORD dst_unused:UNUSED_PAD src0_sel:WORD_1
	v_cvt_f32_f16_e32 v136, v62
	v_or_b32_e32 v57, 16, v57
	v_cvt_f32_f16_sdwa v135, v58 dst_sel:DWORD dst_unused:UNUSED_PAD src0_sel:WORD_1
	v_cvt_f32_f16_e32 v134, v58
	s_waitcnt lgkmcnt(3)
	v_mul_f32_e32 v56, 0x3fb8aa3b, v66
	v_add_u32_e32 v140, s81, v57
	v_add_u32_e32 v141, s0, v57
	v_mul_f32_e32 v57, 0x3fb8aa3b, v67
	v_exp_f32_e32 v56, v56
	v_exp_f32_e32 v57, v57
	v_pk_mul_f32 v[136:137], v[136:137], s[72:73] op_sel_hi:[1,0]
	v_pk_mul_f32 v[134:135], v[134:135], s[72:73] op_sel_hi:[1,0]
	s_waitcnt lgkmcnt(0)
	v_pk_mul_f32 v[136:137], v[136:137], v[126:127]
	v_rcp_f32_e32 v66, v56
	v_cndmask_b32_e64 v137, v137, -v137, s[8:9]
	v_cndmask_b32_e64 v136, v136, -v136, s[8:9]
	v_pk_fma_f32 v[134:135], v[134:135], v[122:123], v[136:137]
	v_cvt_f32_f16_sdwa v137, v48 dst_sel:DWORD dst_unused:UNUSED_PAD src0_sel:WORD_1
	v_pk_mul_f32 v[138:139], v[134:135], v[56:57]
	v_cvt_f32_f16_sdwa v135, v52 dst_sel:DWORD dst_unused:UNUSED_PAD src0_sel:WORD_1
	v_cvt_f32_f16_e32 v134, v52
	v_cvt_f32_f16_e32 v136, v48
	ds_read_b128 v[130:133], v93
	v_rcp_f32_e32 v67, v57
	v_pk_mul_f32 v[126:127], v[126:127], v[134:135]
	v_add3_u32 v52, v72, v89, v247
	v_cndmask_b32_e64 v127, v127, -v127, s[8:9]
	v_cndmask_b32_e64 v126, v126, -v126, s[8:9]
	v_pk_fma_f32 v[122:123], v[122:123], v[136:137], v[126:127]
	ds_read_b128 v[134:137], v94
	v_pk_mul_f32 v[126:127], v[122:123], v[66:67]
	v_cvt_f32_f16_e32 v58, v63
	s_waitcnt lgkmcnt(1)
	v_fma_mixlo_f16 v48, v130, v126, 0
	ds_write_b16 v52, v48 offset:46080
	v_fma_mixlo_f16 v48, v131, v127, 0
	ds_write_b16 v113, v48 offset:46080
	v_mul_f32_e32 v48, 0x3fb8aa3b, v68
	v_exp_f32_e32 v66, v48
	v_mul_f32_e32 v48, 0x3fb8aa3b, v69
	v_cvt_f32_f16_sdwa v69, v59 dst_sel:DWORD dst_unused:UNUSED_PAD src0_sel:WORD_1
	v_cvt_f32_f16_e32 v68, v59
	v_cvt_f32_f16_sdwa v59, v63 dst_sel:DWORD dst_unused:UNUSED_PAD src0_sel:WORD_1
	v_exp_f32_e32 v67, v48
	v_cvt_f32_f16_e32 v52, v49
	v_pk_mul_f32 v[68:69], v[68:69], s[72:73] op_sel_hi:[1,0]
	v_pk_mul_f32 v[58:59], v[58:59], s[72:73] op_sel_hi:[1,0]
	v_rcp_f32_e32 v62, v66
	v_pk_mul_f32 v[58:59], v[58:59], v[128:129]
	v_rcp_f32_e32 v63, v67
	v_cndmask_b32_e64 v59, v59, -v59, s[8:9]
	v_cndmask_b32_e64 v58, v58, -v58, s[8:9]
	v_pk_fma_f32 v[58:59], v[68:69], v[124:125], v[58:59]
	v_cvt_pk_f16_f32 v56, v138, v139
	v_pk_mul_f32 v[130:131], v[58:59], v[66:67]
	v_cvt_f32_f16_sdwa v59, v53 dst_sel:DWORD dst_unused:UNUSED_PAD src0_sel:WORD_1
	v_cvt_f32_f16_e32 v58, v53
	v_cvt_f32_f16_sdwa v53, v49 dst_sel:DWORD dst_unused:UNUSED_PAD src0_sel:WORD_1
	v_cvt_pk_f16_f32 v57, v130, v131
	v_pk_mul_f32 v[48:49], v[128:129], v[58:59]
	s_nop 0
	v_cndmask_b32_e64 v49, v49, -v49, s[8:9]
	v_cndmask_b32_e64 v48, v48, -v48, s[8:9]
	v_pk_fma_f32 v[48:49], v[124:125], v[52:53], v[48:49]
	v_cvt_f32_f16_sdwa v59, v60 dst_sel:DWORD dst_unused:UNUSED_PAD src0_sel:WORD_1
	v_pk_mul_f32 v[48:49], v[48:49], v[62:63]
	v_cvt_f32_f16_sdwa v63, v64 dst_sel:DWORD dst_unused:UNUSED_PAD src0_sel:WORD_1
	v_fma_mixlo_f16 v52, v132, v48, 0
	ds_write_b16 v113, v52 offset:46224
	v_fma_mixlo_f16 v52, v133, v49, 0
	ds_write_b16 v113, v52 offset:46368
	ds_read_b128 v[66:69], v140
	ds_read_b128 v[122:125], v141
	v_cvt_f32_f16_e32 v62, v64
	v_cvt_f32_f16_e32 v58, v60
	v_mul_f32_e32 v52, 0x3fb8aa3b, v118
	v_mul_f32_e32 v53, 0x3fb8aa3b, v119
	v_pk_mul_f32 v[62:63], v[62:63], s[72:73] op_sel_hi:[1,0]
	v_exp_f32_e32 v52, v52
	s_waitcnt lgkmcnt(0)
	v_pk_mul_f32 v[62:63], v[62:63], v[122:123]
	v_exp_f32_e32 v53, v53
	v_pk_mul_f32 v[58:59], v[58:59], s[72:73] op_sel_hi:[1,0]
	v_cndmask_b32_e64 v63, v63, -v63, s[8:9]
	v_cndmask_b32_e64 v62, v62, -v62, s[8:9]
	v_pk_fma_f32 v[58:59], v[58:59], v[66:67], v[62:63]
	v_cvt_f32_f16_sdwa v63, v54 dst_sel:DWORD dst_unused:UNUSED_PAD src0_sel:WORD_1
	v_cvt_f32_f16_e32 v62, v54
	v_cvt_f32_f16_sdwa v129, v50 dst_sel:DWORD dst_unused:UNUSED_PAD src0_sel:WORD_1
	v_cvt_f32_f16_e32 v128, v50
	v_rcp_f32_e32 v118, v52
	v_rcp_f32_e32 v119, v53
	v_pk_mul_f32 v[62:63], v[122:123], v[62:63]
	v_cvt_f32_f16_e32 v60, v65
	v_cndmask_b32_e64 v63, v63, -v63, s[8:9]
	v_cndmask_b32_e64 v62, v62, -v62, s[8:9]
	v_pk_fma_f32 v[62:63], v[66:67], v[128:129], v[62:63]
	v_pk_mul_f32 v[52:53], v[58:59], v[52:53]
	v_pk_mul_f32 v[66:67], v[62:63], v[118:119]
	v_cvt_f32_f16_sdwa v119, v61 dst_sel:DWORD dst_unused:UNUSED_PAD src0_sel:WORD_1
	v_fma_mixlo_f16 v50, v134, v66, 0
	v_cvt_f32_f16_e32 v118, v61
	v_cvt_f32_f16_sdwa v61, v65 dst_sel:DWORD dst_unused:UNUSED_PAD src0_sel:WORD_1
	ds_write_b16 v113, v50 offset:46512
	v_fma_mixlo_f16 v50, v135, v67, 0
	ds_write_b16 v113, v50 offset:46656
	v_mul_f32_e32 v50, 0x3fb8aa3b, v120
	v_exp_f32_e32 v62, v50
	v_mul_f32_e32 v50, 0x3fb8aa3b, v121
	v_exp_f32_e32 v63, v50
	v_pk_mul_f32 v[60:61], v[60:61], s[72:73] op_sel_hi:[1,0]
	v_pk_mul_f32 v[118:119], v[118:119], s[72:73] op_sel_hi:[1,0]
	v_pk_mul_f32 v[60:61], v[60:61], v[124:125]
	v_rcp_f32_e32 v64, v62
	v_cndmask_b32_e64 v61, v61, -v61, s[8:9]
	v_cndmask_b32_e64 v60, v60, -v60, s[8:9]
	v_pk_fma_f32 v[60:61], v[118:119], v[68:69], v[60:61]
	v_rcp_f32_e32 v65, v63
	v_pk_mul_f32 v[60:61], v[60:61], v[62:63]
	v_bfe_u32 v62, v131, 16, 1
	v_bfe_u32 v63, v130, 16, 1
	v_bfe_u32 v75, v53, 16, 1
	v_bfe_u32 v79, v52, 16, 1
	v_cvt_pk_f16_f32 v58, v52, v53
	v_bfe_u32 v50, v61, 16, 1
	v_add3_u32 v120, v130, v63, s34
	v_add3_u32 v62, v131, v62, s34
	v_add3_u32 v52, v52, v79, s34
	v_add3_u32 v53, v53, v75, s34
	v_cvt_pk_f16_f32 v59, v60, v61
	v_bfe_u32 v54, v60, 16, 1
	v_add3_u32 v50, v61, v50, s34
	v_perm_b32 v61, v62, v120, s35
	v_perm_b32 v62, v53, v52, s35
	v_cvt_f32_f16_sdwa v53, v55 dst_sel:DWORD dst_unused:UNUSED_PAD src0_sel:WORD_1
	v_cvt_f32_f16_e32 v52, v55
	v_add3_u32 v54, v60, v54, s34
	v_perm_b32 v63, v50, v54, s35
	v_cvt_f32_f16_sdwa v55, v51 dst_sel:DWORD dst_unused:UNUSED_PAD src0_sel:WORD_1
	v_cvt_f32_f16_e32 v54, v51
	v_pk_mul_f32 v[50:51], v[124:125], v[52:53]
	v_bfe_u32 v118, v139, 16, 1
	v_cndmask_b32_e64 v51, v51, -v51, s[8:9]
	v_cndmask_b32_e64 v50, v50, -v50, s[8:9]
	v_pk_fma_f32 v[50:51], v[68:69], v[54:55], v[50:51]
	v_bfe_u32 v119, v138, 16, 1
	v_pk_mul_f32 v[52:53], v[50:51], v[64:65]
	v_bfe_u32 v51, v48, 16, 1
	v_fma_mixlo_f16 v50, v136, v52, 0
	v_bfe_u32 v54, v53, 16, 1
	v_bfe_u32 v55, v52, 16, 1
	ds_write_b16 v113, v50 offset:46800
	v_bfe_u32 v50, v49, 16, 1
	v_bfe_u32 v64, v67, 16, 1
	v_bfe_u32 v65, v66, 16, 1
	v_bfe_u32 v68, v127, 16, 1
	v_bfe_u32 v69, v126, 16, 1
	v_add3_u32 v52, v52, v55, s34
	v_add3_u32 v54, v53, v54, s34
	v_add3_u32 v60, v138, v119, s34
	v_add3_u32 v118, v139, v118, s34
	v_add3_u32 v48, v48, v51, s34
	v_add3_u32 v49, v49, v50, s34
	v_add3_u32 v55, v126, v69, s34
	v_add3_u32 v68, v127, v68, s34
	v_add3_u32 v50, v66, v65, s34
	v_add3_u32 v64, v67, v64, s34
	v_perm_b32 v51, v54, v52, s35
	v_fma_mixlo_f16 v52, v137, v53, 0
	v_perm_b32 v60, v118, v60, s35
	v_perm_b32 v49, v49, v48, s35
	v_perm_b32 v50, v64, v50, s35
	v_perm_b32 v48, v68, v55, s35
	ds_write_b16 v113, v52 offset:46944
	ds_write_b128 v83, v[60:63] offset:18432
	ds_write_b128 v83, v[48:51] offset:27648
	ds_write_b128 v83, v[56:59] offset:36864
	v_add_u32_e32 v56, v73, v0
	s_waitcnt lgkmcnt(0)
	s_barrier
	ds_read_b128 v[48:51], v56
	v_add_u32_e32 v68, v86, v95
	ds_read_b128 v[52:55], v68 offset:36864
	ds_read_b128 v[64:67], v56 offset:64
	ds_read_b128 v[56:59], v68 offset:36928
	ds_read_b128 v[60:63], v68 offset:39168
	ds_read_b128 v[118:121], v68 offset:39232
	ds_read_b128 v[122:125], v68 offset:41472
	ds_read_b128 v[126:129], v68 offset:41536
	ds_read_b128 v[130:133], v68 offset:43776
	ds_read_b128 v[134:137], v68 offset:43840
	s_waitcnt lgkmcnt(8)
	v_mfma_f32_16x16x32_f16 v[52:55], v[48:51], v[52:55], 0
	v_add_u32_e32 v75, v92, v0
	v_mov_b32_e32 v68, 0
	v_mov_b32_e32 v69, 0
	s_waitcnt lgkmcnt(5)
	v_mfma_f32_16x16x32_f16 v[60:63], v[48:51], v[60:63], 0
	s_waitcnt lgkmcnt(3)
	v_mfma_f32_16x16x32_f16 v[122:125], v[48:51], v[122:125], 0
	s_waitcnt lgkmcnt(1)
	v_mfma_f32_16x16x32_f16 v[48:51], v[48:51], v[130:133], 0
	v_mfma_f32_16x16x32_f16 v[52:55], v[64:67], v[56:59], v[52:55]
	v_mfma_f32_16x16x32_f16 v[56:59], v[64:67], v[118:121], v[60:63]
	v_mfma_f32_16x16x32_f16 v[60:63], v[64:67], v[126:129], v[122:125]
	s_waitcnt lgkmcnt(0)
	v_mfma_f32_16x16x32_f16 v[48:51], v[64:67], v[134:137], v[48:51]
	v_mov_b32_e32 v64, 0
	v_mov_b32_e32 v66, 0
	v_mov_b32_e32 v67, 0
	s_and_saveexec_b64 s[0:1], s[10:11]
	s_cbranch_execz .LBB0_1009
	v_add_u32_e32 v65, v86, v98
	ds_read_b128 v[66:69], v75 offset:18432
	ds_read_b128 v[118:121], v65 offset:27648
	s_waitcnt lgkmcnt(0)
	v_mfma_f32_16x16x32_bf16 v[66:69], v[118:121], v[66:69], 0
	ds_read_b128 v[118:121], v75 offset:18496
	ds_read_b128 v[122:125], v65 offset:27712
	s_waitcnt lgkmcnt(0)
	v_mfma_f32_16x16x32_bf16 v[66:69], v[122:125], v[118:121], v[66:69]
